# speedup vs baseline: 1.0062x; 1.0057x over previous
; __device__ __forceinline__ void phase_prep(const Params& p, char* smraw) {
;     ...
;           const int q0 = __float2int_rn(v[j][0] * inv) + 8, q1 = __float2int_rn(v[j][1] * inv) + 8, q2 = __float2int_rn(v[j][2] * inv) + 8, q3 = __float2int_rn(v[j][3] * inv) + 8;
;           const int own = (q0 & 15) | ((q1 & 15) << 8) | ((q2 & 15) << 16) | ((q3 & 15) << 24);
;           const int nb2 = __shfl_xor(own, 1);
;           if ((l & 1) == 0) *(int*)(p.Uq + ((size_t)(ly * 4 + j) * NEXP + e) * 128 + (l >> 1) * 4) = own | (nb2 << 4);
.LBB0_73:
	s_andn2_saveexec_b64 s[20:21], s[20:21]
	s_cbranch_execz .LBB0_77
	v_rndne_f32_e32 v33, v64
	v_rndne_f32_e32 v32, v47
	v_cvt_i32_f32_e32 v33, v33
	v_rndne_f32_e32 v30, v30
	v_cvt_i32_f32_e32 v32, v32
	v_cvt_i32_f32_sdwa v30, v30 dst_sel:WORD_1 dst_unused:UNUSED_PAD src0_sel:DWORD
	v_rndne_f32_e32 v31, v31
	v_cvt_i32_f32_sdwa v31, v31 dst_sel:BYTE_3 dst_unused:UNUSED_PAD src0_sel:DWORD
	v_lshlrev_b32_e32 v33, 8, v33
	v_and_b32_e32 v32, 15, v32
	v_and_b32_e32 v33, 0xf00, v33
	v_and_b32_e32 v30, 0xf0000, v30
	v_or3_b32 v30, v33, v32, v30
	v_and_b32_e32 v31, 0xf000000, v31
	v_bitop3_b32 v30, v30, s28, v31 bitop3:0x36
	ds_bpermute_b32 v31, v52, v30
	s_and_saveexec_b64 s[22:23], s[4:5]
	s_cbranch_execz .LBB0_76
	v_ashrrev_i32_e32 v47, 31, v46
	v_lshlrev_b64 v[32:33], 21, v[46:47]
	v_lshl_add_u64 v[32:33], s[88:89], 0, v[32:33]
	v_lshl_add_u64 v[32:33], v[32:33], 0, v[44:45]
	v_lshl_add_u64 v[32:33], v[32:33], 0, v[36:37]
	s_waitcnt lgkmcnt(0)
	v_lshl_or_b32 v30, v31, 4, v30
	v_xor_b32_e32 v30, 0x80808080, v30
	global_store_dword v[32:33], v30, off

; __device__ __forceinline__ void phase_prep(const Params& p, char* smraw) {
;     ...
;           const int q0 = __float2int_rn(v[j][0] * inv) + 8, q1 = __float2int_rn(v[j][1] * inv) + 8, q2 = __float2int_rn(v[j][2] * inv) + 8, q3 = __float2int_rn(v[j][3] * inv) + 8;
;           const int own = (q0 & 15) | ((q1 & 15) << 8) | ((q2 & 15) << 16) | ((q3 & 15) << 24);
;           const int nb2 = __shfl_xor(own, 1);
;           if ((l & 1) == 0) *(int*)(p.Uq + ((size_t)(ly * 4 + j) * NEXP + e) * 128 + (l >> 1) * 4) = own | (nb2 << 4);
.LBB0_79:
	s_andn2_saveexec_b64 s[20:21], s[20:21]
	s_cbranch_execz .LBB0_83
	v_rndne_f32_e32 v29, v31
	v_rndne_f32_e32 v28, v30
	v_cvt_i32_f32_e32 v29, v29
	v_rndne_f32_e32 v26, v26
	v_cvt_i32_f32_e32 v28, v28
	v_cvt_i32_f32_sdwa v26, v26 dst_sel:WORD_1 dst_unused:UNUSED_PAD src0_sel:DWORD
	v_rndne_f32_e32 v27, v27
	v_cvt_i32_f32_sdwa v27, v27 dst_sel:BYTE_3 dst_unused:UNUSED_PAD src0_sel:DWORD
	v_lshlrev_b32_e32 v29, 8, v29
	v_and_b32_e32 v28, 15, v28
	v_and_b32_e32 v29, 0xf00, v29
	v_and_b32_e32 v26, 0xf0000, v26
	v_or3_b32 v26, v29, v28, v26
	v_and_b32_e32 v27, 0xf000000, v27
	v_bitop3_b32 v26, v26, s28, v27 bitop3:0x36
	ds_bpermute_b32 v27, v52, v26
	s_and_saveexec_b64 s[22:23], s[4:5]
	s_cbranch_execz .LBB0_82
	s_waitcnt lgkmcnt(0)
	v_lshl_or_b32 v28, v27, 4, v26
	v_xor_b32_e32 v28, 0x80808080, v28
	v_or_b32_e32 v26, 1, v46
	v_ashrrev_i32_e32 v27, 31, v26
	v_lshlrev_b64 v[26:27], 21, v[26:27]
	v_lshl_add_u64 v[26:27], s[88:89], 0, v[26:27]
	v_lshl_add_u64 v[26:27], v[26:27], 0, v[44:45]
	v_lshl_add_u64 v[26:27], v[26:27], 0, v[36:37]
	global_store_dword v[26:27], v28, off

; __device__ __forceinline__ void phase_prep(const Params& p, char* smraw) {
;     ...
;           const int q0 = __float2int_rn(v[j][0] * inv) + 8, q1 = __float2int_rn(v[j][1] * inv) + 8, q2 = __float2int_rn(v[j][2] * inv) + 8, q3 = __float2int_rn(v[j][3] * inv) + 8;
;           const int own = (q0 & 15) | ((q1 & 15) << 8) | ((q2 & 15) << 16) | ((q3 & 15) << 24);
;           const int nb2 = __shfl_xor(own, 1);
;           if ((l & 1) == 0) *(int*)(p.Uq + ((size_t)(ly * 4 + j) * NEXP + e) * 128 + (l >> 1) * 4) = own | (nb2 << 4);
.LBB0_85:
	s_andn2_saveexec_b64 s[20:21], s[20:21]
	s_cbranch_execz .LBB0_89
	v_rndne_f32_e32 v25, v27
	v_rndne_f32_e32 v24, v26
	v_cvt_i32_f32_e32 v25, v25
	v_rndne_f32_e32 v22, v22
	v_cvt_i32_f32_e32 v24, v24
	v_cvt_i32_f32_sdwa v22, v22 dst_sel:WORD_1 dst_unused:UNUSED_PAD src0_sel:DWORD
	v_rndne_f32_e32 v23, v23
	v_cvt_i32_f32_sdwa v23, v23 dst_sel:BYTE_3 dst_unused:UNUSED_PAD src0_sel:DWORD
	v_lshlrev_b32_e32 v25, 8, v25
	v_and_b32_e32 v24, 15, v24
	v_and_b32_e32 v25, 0xf00, v25
	v_and_b32_e32 v22, 0xf0000, v22
	v_or3_b32 v22, v25, v24, v22
	v_and_b32_e32 v23, 0xf000000, v23
	v_bitop3_b32 v22, v22, s28, v23 bitop3:0x36
	ds_bpermute_b32 v23, v52, v22
	s_and_saveexec_b64 s[22:23], s[4:5]
	s_cbranch_execz .LBB0_88
	s_waitcnt lgkmcnt(0)
	v_lshl_or_b32 v24, v23, 4, v22
	v_xor_b32_e32 v24, 0x80808080, v24
	v_or_b32_e32 v22, 2, v46
	v_ashrrev_i32_e32 v23, 31, v22
	v_lshlrev_b64 v[22:23], 21, v[22:23]
	v_lshl_add_u64 v[22:23], s[88:89], 0, v[22:23]
	v_lshl_add_u64 v[22:23], v[22:23], 0, v[44:45]
	v_lshl_add_u64 v[22:23], v[22:23], 0, v[36:37]
	global_store_dword v[22:23], v24, off

; __device__ __forceinline__ void phase_prep(const Params& p, char* smraw) {
;     ...
;           const int q0 = __float2int_rn(v[j][0] * inv) + 8, q1 = __float2int_rn(v[j][1] * inv) + 8, q2 = __float2int_rn(v[j][2] * inv) + 8, q3 = __float2int_rn(v[j][3] * inv) + 8;
;           const int own = (q0 & 15) | ((q1 & 15) << 8) | ((q2 & 15) << 16) | ((q3 & 15) << 24);
;           const int nb2 = __shfl_xor(own, 1);
;           if ((l & 1) == 0) *(int*)(p.Uq + ((size_t)(ly * 4 + j) * NEXP + e) * 128 + (l >> 1) * 4) = own | (nb2 << 4);
.LBB0_97:
	v_rndne_f32_e32 v21, v23
	v_rndne_f32_e32 v20, v22
	v_cvt_i32_f32_e32 v21, v21
	v_rndne_f32_e32 v18, v18
	v_cvt_i32_f32_e32 v20, v20
	v_cvt_i32_f32_sdwa v18, v18 dst_sel:WORD_1 dst_unused:UNUSED_PAD src0_sel:DWORD
	v_rndne_f32_e32 v19, v19
	v_cvt_i32_f32_sdwa v19, v19 dst_sel:BYTE_3 dst_unused:UNUSED_PAD src0_sel:DWORD
	v_lshlrev_b32_e32 v21, 8, v21
	v_and_b32_e32 v20, 15, v20
	v_and_b32_e32 v21, 0xf00, v21
	v_and_b32_e32 v18, 0xf0000, v18
	v_or3_b32 v18, v21, v20, v18
	v_and_b32_e32 v19, 0xf000000, v19
	v_bitop3_b32 v18, v18, s28, v19 bitop3:0x36
	ds_bpermute_b32 v19, v52, v18
	s_and_saveexec_b64 s[20:21], s[4:5]
	s_cbranch_execz .LBB0_99
	s_waitcnt lgkmcnt(0)
	v_lshl_or_b32 v20, v19, 4, v18
	v_xor_b32_e32 v20, 0x80808080, v20
	v_or_b32_e32 v18, 3, v46
	v_ashrrev_i32_e32 v19, 31, v18
	v_lshlrev_b64 v[18:19], 21, v[18:19]
	v_lshl_add_u64 v[18:19], s[88:89], 0, v[18:19]
	v_lshl_add_u64 v[18:19], v[18:19], 0, v[44:45]
	v_lshl_add_u64 v[18:19], v[18:19], 0, v[36:37]
	global_store_dword v[18:19], v20, off

; __device__ __forceinline__ void phase_prep(const Params& p, char* smraw) {
;     ...
;           const int q0 = __float2int_rn(v[j][0] * inv) + 8, q1 = __float2int_rn(v[j][1] * inv) + 8, q2 = __float2int_rn(v[j][2] * inv) + 8, q3 = __float2int_rn(v[j][3] * inv) + 8;
;           const int own = (q0 & 15) | ((q1 & 15) << 8) | ((q2 & 15) << 16) | ((q3 & 15) << 24);
;           const int nb2 = __shfl_xor(own, 1);
;           if ((l & 1) == 0) *(int*)(p.Uq + ((size_t)(ly * 4 + j) * NEXP + e) * 128 + (l >> 1) * 4) = own | (nb2 << 4);
.LBB0_108:
	s_andn2_saveexec_b64 s[20:21], s[20:21]
	s_cbranch_execz .LBB0_112
	v_rndne_f32_e32 v17, v26
	v_rndne_f32_e32 v16, v23
	v_cvt_i32_f32_e32 v17, v17
	v_rndne_f32_e32 v14, v14
	v_cvt_i32_f32_e32 v16, v16
	v_cvt_i32_f32_sdwa v14, v14 dst_sel:WORD_1 dst_unused:UNUSED_PAD src0_sel:DWORD
	v_rndne_f32_e32 v15, v15
	v_cvt_i32_f32_sdwa v15, v15 dst_sel:BYTE_3 dst_unused:UNUSED_PAD src0_sel:DWORD
	v_lshlrev_b32_e32 v17, 8, v17
	v_and_b32_e32 v16, 15, v16
	v_and_b32_e32 v17, 0xf00, v17
	v_and_b32_e32 v14, 0xf0000, v14
	v_or3_b32 v14, v17, v16, v14
	v_and_b32_e32 v15, 0xf000000, v15
	v_bitop3_b32 v14, v14, s28, v15 bitop3:0x36
	ds_bpermute_b32 v15, v52, v14
	s_and_saveexec_b64 s[22:23], s[4:5]
	s_cbranch_execz .LBB0_111
	v_ashrrev_i32_e32 v23, 31, v22
	v_lshlrev_b64 v[16:17], 21, v[22:23]
	v_lshl_add_u64 v[16:17], s[88:89], 0, v[16:17]
	v_lshl_add_u64 v[16:17], v[16:17], 0, v[20:21]
	v_lshl_add_u64 v[16:17], v[16:17], 0, v[36:37]
	s_waitcnt lgkmcnt(0)
	v_lshl_or_b32 v14, v15, 4, v14
	v_xor_b32_e32 v14, 0x80808080, v14
	global_store_dword v[16:17], v14, off

; __device__ __forceinline__ void phase_prep(const Params& p, char* smraw) {
;     ...
;           const int q0 = __float2int_rn(v[j][0] * inv) + 8, q1 = __float2int_rn(v[j][1] * inv) + 8, q2 = __float2int_rn(v[j][2] * inv) + 8, q3 = __float2int_rn(v[j][3] * inv) + 8;
;           const int own = (q0 & 15) | ((q1 & 15) << 8) | ((q2 & 15) << 16) | ((q3 & 15) << 24);
;           const int nb2 = __shfl_xor(own, 1);
;           if ((l & 1) == 0) *(int*)(p.Uq + ((size_t)(ly * 4 + j) * NEXP + e) * 128 + (l >> 1) * 4) = own | (nb2 << 4);
.LBB0_114:
	s_andn2_saveexec_b64 s[20:21], s[20:21]
	s_cbranch_execz .LBB0_118
	v_rndne_f32_e32 v13, v15
	v_rndne_f32_e32 v12, v14
	v_cvt_i32_f32_e32 v13, v13
	v_rndne_f32_e32 v10, v10
	v_cvt_i32_f32_e32 v12, v12
	v_cvt_i32_f32_sdwa v10, v10 dst_sel:WORD_1 dst_unused:UNUSED_PAD src0_sel:DWORD
	v_rndne_f32_e32 v11, v11
	v_cvt_i32_f32_sdwa v11, v11 dst_sel:BYTE_3 dst_unused:UNUSED_PAD src0_sel:DWORD
	v_lshlrev_b32_e32 v13, 8, v13
	v_and_b32_e32 v12, 15, v12
	v_and_b32_e32 v13, 0xf00, v13
	v_and_b32_e32 v10, 0xf0000, v10
	v_or3_b32 v10, v13, v12, v10
	v_and_b32_e32 v11, 0xf000000, v11
	v_bitop3_b32 v10, v10, s28, v11 bitop3:0x36
	ds_bpermute_b32 v11, v52, v10
	s_and_saveexec_b64 s[22:23], s[4:5]
	s_cbranch_execz .LBB0_117
	s_waitcnt lgkmcnt(0)
	v_lshl_or_b32 v12, v11, 4, v10
	v_xor_b32_e32 v12, 0x80808080, v12
	v_or_b32_e32 v10, 1, v22
	v_ashrrev_i32_e32 v11, 31, v10
	v_lshlrev_b64 v[10:11], 21, v[10:11]
	v_lshl_add_u64 v[10:11], s[88:89], 0, v[10:11]
	v_lshl_add_u64 v[10:11], v[10:11], 0, v[20:21]
	v_lshl_add_u64 v[10:11], v[10:11], 0, v[36:37]
	global_store_dword v[10:11], v12, off

; __device__ __forceinline__ void phase_prep(const Params& p, char* smraw) {
;     ...
;           const int q0 = __float2int_rn(v[j][0] * inv) + 8, q1 = __float2int_rn(v[j][1] * inv) + 8, q2 = __float2int_rn(v[j][2] * inv) + 8, q3 = __float2int_rn(v[j][3] * inv) + 8;
;           const int own = (q0 & 15) | ((q1 & 15) << 8) | ((q2 & 15) << 16) | ((q3 & 15) << 24);
;           const int nb2 = __shfl_xor(own, 1);
;           if ((l & 1) == 0) *(int*)(p.Uq + ((size_t)(ly * 4 + j) * NEXP + e) * 128 + (l >> 1) * 4) = own | (nb2 << 4);
.LBB0_120:
	s_andn2_saveexec_b64 s[20:21], s[20:21]
	s_cbranch_execz .LBB0_124
	v_rndne_f32_e32 v9, v11
	v_rndne_f32_e32 v8, v10
	v_cvt_i32_f32_e32 v9, v9
	v_rndne_f32_e32 v6, v6
	v_cvt_i32_f32_e32 v8, v8
	v_cvt_i32_f32_sdwa v6, v6 dst_sel:WORD_1 dst_unused:UNUSED_PAD src0_sel:DWORD
	v_rndne_f32_e32 v7, v7
	v_cvt_i32_f32_sdwa v7, v7 dst_sel:BYTE_3 dst_unused:UNUSED_PAD src0_sel:DWORD
	v_lshlrev_b32_e32 v9, 8, v9
	v_and_b32_e32 v8, 15, v8
	v_and_b32_e32 v9, 0xf00, v9
	v_and_b32_e32 v6, 0xf0000, v6
	v_or3_b32 v6, v9, v8, v6
	v_and_b32_e32 v7, 0xf000000, v7
	v_bitop3_b32 v6, v6, s28, v7 bitop3:0x36
	ds_bpermute_b32 v7, v52, v6
	s_and_saveexec_b64 s[22:23], s[4:5]
	s_cbranch_execz .LBB0_123
	s_waitcnt lgkmcnt(0)
	v_lshl_or_b32 v8, v7, 4, v6
	v_xor_b32_e32 v8, 0x80808080, v8
	v_or_b32_e32 v6, 2, v22
	v_ashrrev_i32_e32 v7, 31, v6
	v_lshlrev_b64 v[6:7], 21, v[6:7]
	v_lshl_add_u64 v[6:7], s[88:89], 0, v[6:7]
	v_lshl_add_u64 v[6:7], v[6:7], 0, v[20:21]
	v_lshl_add_u64 v[6:7], v[6:7], 0, v[36:37]
	global_store_dword v[6:7], v8, off

; __device__ __forceinline__ void phase_prep(const Params& p, char* smraw) {
;     ...
;           const int q0 = __float2int_rn(v[j][0] * inv) + 8, q1 = __float2int_rn(v[j][1] * inv) + 8, q2 = __float2int_rn(v[j][2] * inv) + 8, q3 = __float2int_rn(v[j][3] * inv) + 8;
;           const int own = (q0 & 15) | ((q1 & 15) << 8) | ((q2 & 15) << 16) | ((q3 & 15) << 24);
;           const int nb2 = __shfl_xor(own, 1);
;           if ((l & 1) == 0) *(int*)(p.Uq + ((size_t)(ly * 4 + j) * NEXP + e) * 128 + (l >> 1) * 4) = own | (nb2 << 4);
.LBB0_131:
	v_rndne_f32_e32 v5, v7
	v_rndne_f32_e32 v4, v6
	v_cvt_i32_f32_e32 v5, v5
	v_rndne_f32_e32 v2, v2
	v_cvt_i32_f32_e32 v4, v4
	v_cvt_i32_f32_sdwa v2, v2 dst_sel:WORD_1 dst_unused:UNUSED_PAD src0_sel:DWORD
	v_rndne_f32_e32 v3, v3
	v_cvt_i32_f32_sdwa v3, v3 dst_sel:BYTE_3 dst_unused:UNUSED_PAD src0_sel:DWORD
	v_lshlrev_b32_e32 v5, 8, v5
	v_and_b32_e32 v4, 15, v4
	v_and_b32_e32 v5, 0xf00, v5
	v_and_b32_e32 v2, 0xf0000, v2
	v_or3_b32 v2, v5, v4, v2
	v_and_b32_e32 v3, 0xf000000, v3
	v_bitop3_b32 v2, v2, s28, v3 bitop3:0x36
	ds_bpermute_b32 v3, v52, v2
	s_and_saveexec_b64 s[20:21], s[4:5]
	s_cbranch_execz .LBB0_133
	s_waitcnt lgkmcnt(0)
	v_lshl_or_b32 v4, v3, 4, v2
	v_xor_b32_e32 v4, 0x80808080, v4
	v_or_b32_e32 v2, 3, v22
	v_ashrrev_i32_e32 v3, 31, v2
	v_lshlrev_b64 v[2:3], 21, v[2:3]
	v_lshl_add_u64 v[2:3], s[88:89], 0, v[2:3]
	v_lshl_add_u64 v[2:3], v[2:3], 0, v[20:21]
	v_lshl_add_u64 v[2:3], v[2:3], 0, v[36:37]
	global_store_dword v[2:3], v4, off

; __device__ __forceinline__ int tid_opaque() { int t = threadIdx.x; asm volatile("" : "+v"(t)); return t; }
; __device__ __forceinline__ void phase_peer_u(const Params& p, int layer, int xs, int wid0, int wstride, char* smraw) {
;   const int tid = tid_opaque(), l = tid & 63, g = l >> 3, j = l & 7;
;   const int wid = wid0 + (tid >> 6);
;   char* xqs = smraw + (tid >> 6) * 256;
;   const int sl = xs >> 1, par = xs & 1;
;   constexpr int TH = T / 2;
;   const unsigned char* Uq = p.Uq + (size_t)(layer * 4 + sl) * NEXP * 128;
;   const unsigned joff = j * 16;
;   u32x4 ni[4];
;   auto load_idx = [&](int tt) {
;     const u32x4* ip = (const u32x4*)((const char*)p.sel_idx + ((unsigned)(2 * tt + par) * 512u + (unsigned)g * 64u));
; #pragma unroll
;     for (int q4 = 0; q4 < 4; ++q4) ni[q4] = ip[q4];
;   };
;   auto issue_rows = [&](int tt, u32x4 (&q)[16], u32x2& xv) {
; #pragma unroll
;     for (int i = 0; i < 16; ++i) q[i] = *(const u32x4*)(Uq + (ni[i >> 2][i & 3] * 128u + joff));
;     xv = *(const u32x2*)((const char*)p.hb + ((unsigned)(2 * tt + par) * 2048u + (unsigned)(sl * 512 + l * 8)));
;   };
;     ...
;   u32x4 qA[16], qB[16]; u32x2 xA = {0u, 0u}, xB = {0u, 0u};
;   int tt = wid;
;   if (tt < TH) { load_idx(tt); issue_rows(tt, qA, xA); if (tt + wstride < TH) load_idx(tt + wstride); }
.LBB0_670:
	s_or_b64 exec, exec, s[0:1]
	v_mov_b32_e32 v16, v189
	s_barrier
	s_ashr_i32 s14, s3, 1
	s_waitcnt vmcnt(5)
	v_ashrrev_i32_e32 v80, 6, v16
	v_add_u32_e32 v169, s92, v80
	s_and_b32 s28, s3, 1
	s_ashr_i32 s15, s14, 31
	s_movk_i32 s3, 0x4020
	s_lshl_b64 s[0:1], s[14:15], 21
	v_cmp_gt_i32_e32 vcc, s3, v169
	s_mul_i32 s29, s33, 3
	s_and_saveexec_b64 s[8:9], vcc
	s_cbranch_execz .LBB0_689
	v_and_b32_e32 v6, 63, v189
	v_lshrrev_b32_e32 v7, 6, v189
	v_lshlrev_b32_e32 v0, 3, v6
	v_and_b32_e32 v1, 7, v6
	v_cmp_eq_u32_e64 s[72:73], 0, v1
	v_lshlrev_b32_e32 v1, 4, v1
	v_lshrrev_b32_e32 v8, 3, v6
	v_readfirstlane_b32 s70, v7
	s_lshl_b32 s71, s28, 9
	v_lshl_add_u32 v2, v8, 6, s71
	v_lshlrev_b32_e32 v5, 6, v8
	v_lshlrev_b32_e32 v3, 8, v7
	v_lshl_add_u32 v4, v1, 1, v3
	v_lshl_add_u32 v3, v6, 2, v3
	s_add_u32 s60, s92, s70
	s_movk_i32 s61, 0x4020
	s_cmp_ge_u32 s60, s61
	s_cbranch_scc1 .Lmy_pu0_done
	s_lshl_b32 s70, s14, 21
	s_add_u32 s66, s88, s70
	s_addc_u32 s67, s89, 0
	v_readlane_b32 s64, v254, 4
	v_readlane_b32 s65, v254, 5
	s_lshl_b32 s68, s14, 9
	s_mov_b32 s69, 0x42fe0000
	s_mov_b32 s21, 0xf0f0f0f
	s_mov_b32 s23, 0xf0f0f0f0
	s_lshl_b32 s70, s60, 10
	v_add_u32_e32 v9, s70, v2
	global_load_dwordx4 v[10:13], v9, s[52:53]
	global_load_dwordx4 v[14:17], v9, s[52:53] offset:16
	global_load_dwordx4 v[18:21], v9, s[52:53] offset:32
	global_load_dwordx4 v[22:25], v9, s[52:53] offset:48
	s_waitcnt vmcnt(0)
	v_lshl_add_u32 v6, v10, 7, v1
	global_load_dwordx4 v[106:109], v6, s[66:67]
	v_lshl_add_u32 v7, v11, 7, v1
	global_load_dwordx4 v[110:113], v7, s[66:67]
	v_lshl_add_u32 v6, v12, 7, v1
	global_load_dwordx4 v[114:117], v6, s[66:67]
	v_lshl_add_u32 v7, v13, 7, v1
	global_load_dwordx4 v[118:121], v7, s[66:67]
	v_lshl_add_u32 v6, v14, 7, v1
	global_load_dwordx4 v[122:125], v6, s[66:67]
	v_lshl_add_u32 v7, v15, 7, v1
	global_load_dwordx4 v[126:129], v7, s[66:67]
	v_lshl_add_u32 v6, v16, 7, v1
	global_load_dwordx4 v[130:133], v6, s[66:67]
	v_lshl_add_u32 v7, v17, 7, v1
	global_load_dwordx4 v[134:137], v7, s[66:67]
	v_lshl_add_u32 v6, v18, 7, v1
	global_load_dwordx4 v[138:141], v6, s[66:67]
	v_lshl_add_u32 v7, v19, 7, v1
	global_load_dwordx4 v[142:145], v7, s[66:67]
	v_lshl_add_u32 v6, v20, 7, v1
	global_load_dwordx4 v[146:149], v6, s[66:67]
	v_lshl_add_u32 v7, v21, 7, v1
	global_load_dwordx4 v[150:153], v7, s[66:67]
	v_lshl_add_u32 v6, v22, 7, v1
	global_load_dwordx4 v[154:157], v6, s[66:67]
	v_lshl_add_u32 v7, v23, 7, v1
	global_load_dwordx4 v[158:161], v7, s[66:67]
	v_lshl_add_u32 v6, v24, 7, v1
	global_load_dwordx4 v[162:165], v6, s[66:67]
	v_lshl_add_u32 v7, v25, 7, v1
	global_load_dwordx4 v[166:169], v7, s[66:67]
	s_lshl_b32 s70, s60, 1
	s_add_u32 s70, s70, s28
	s_lshl_b32 s70, s70, 11
	s_add_u32 s70, s70, s68
	v_add_u32_e32 v8, s70, v0
	global_load_dwordx2 v[26:27], v8, s[76:77]
	s_add_u32 s62, s60, s33
	s_cmp_ge_u32 s62, s61
	s_cbranch_scc1 .Lmy_pu0_pro1
	s_lshl_b32 s70, s62, 10
	v_add_u32_e32 v9, s70, v2
	global_load_dwordx4 v[10:13], v9, s[52:53]
	global_load_dwordx4 v[14:17], v9, s[52:53] offset:16
	global_load_dwordx4 v[18:21], v9, s[52:53] offset:32
	global_load_dwordx4 v[22:25], v9, s[52:53] offset:48

; __device__ __forceinline__ float bflo(unsigned u) { return __uint_as_float(u << 16); }
; __device__ __forceinline__ float bfhi(unsigned u) { return __uint_as_float(u & 0xffff0000u); }
; __device__ __forceinline__ void phase_peer_u(const Params& p, int layer, int xs, int wid0, int wstride, char* smraw) {
;     ...
;     int xq[8]; float sx; int sumx = 0;
;     {
;       const float x0 = bflo(xv[0]), x1 = bfhi(xv[0]), x2 = bflo(xv[1]), x3 = bfhi(xv[1]);
;       float mx = fmaxf(fmaxf(fabsf(x0), fabsf(x1)), fmaxf(fabsf(x2), fabsf(x3)));
; #pragma unroll
;       for (int m = 32; m >= 1; m >>= 1) mx = fmaxf(mx, __shfl_xor(mx, m));
;       const float inv = mx > 0.f ? 127.f / mx : 0.f;
;       sx = mx * (1.f / 127.f);
;       const int q0 = __float2int_rn(x0 * inv), q1 = __float2int_rn(x1 * inv), q2 = __float2int_rn(x2 * inv), q3 = __float2int_rn(x3 * inv);
;       asm volatile("" ::: "memory");
;       *(int*)(xqs + l * 4) = (q0 & 0xff) | ((q1 & 0xff) << 8) | ((q2 & 0xff) << 16) | ((q3 & 0xff) << 24);
;       asm volatile("" ::: "memory");
;       __builtin_amdgcn_wave_barrier();
;       asm volatile("" ::: "memory");
;       const u32x4 xa = *(const u32x4*)(xqs + j * 32), xb = *(const u32x4*)(xqs + j * 32 + 16);
;       asm volatile("" ::: "memory");
; #pragma unroll
;       for (int m = 0; m < 4; ++m) { xq[m] = (int)xa[m]; xq[4 + m] = (int)xb[m]; }
; #pragma unroll
;       for (int m = 0; m < 8; ++m) sumx = __builtin_amdgcn_sdot4(xq[m], 0x01010101, sumx, false);
;     }
;     const int corr = 8 * sumx;
;     float pr[16];
; #pragma unroll
;     for (int i = 0; i < 16; ++i) {
;       int a = 0;
; #pragma unroll
;       for (int m = 0; m < 4; ++m) {
;         const unsigned dw = q[i][m];
;         a = __builtin_amdgcn_sdot4((int)(dw & 0x0f0f0f0fu), xq[2 * m], a, false);
;         a = __builtin_amdgcn_sdot4((int)((dw >> 4) & 0x0f0f0f0fu), xq[2 * m + 1], a, false);
;       }
;       a -= corr;
;       a += __builtin_amdgcn_update_dpp(0, a, 0xB1, 0xF, 0xF, true);
;       a += __builtin_amdgcn_update_dpp(0, a, 0x4E, 0xF, 0xF, true);
;       a += __builtin_amdgcn_update_dpp(0, a, 0x141, 0xF, 0xF, true);
;       pr[i] = (float)a * sx;
;     }
.Lmy_pu0_noissueA:
	v_lshlrev_b32_e32 v40, 16, v26
	v_and_b32_e32 v41, 0xffff0000, v26
	v_lshlrev_b32_e32 v42, 16, v27
	v_and_b32_e32 v43, 0xffff0000, v27
	v_max_f32_e64 v44, |v40|, |v41|
	v_max3_f32 v44, |v42|, |v43|, v44
	s_nop 1
	v_max_f32_dpp v44, v44, v44 quad_perm:[1,0,3,2] row_mask:0xf bank_mask:0xf bound_ctrl:1
	s_nop 1
	v_max_f32_dpp v44, v44, v44 quad_perm:[2,3,0,1] row_mask:0xf bank_mask:0xf bound_ctrl:1
	s_nop 1
	v_max_f32_dpp v44, v44, v44 row_half_mirror row_mask:0xf bank_mask:0xf bound_ctrl:1
	s_nop 1
	v_max_f32_dpp v44, v44, v44 row_mirror row_mask:0xf bank_mask:0xf bound_ctrl:1
	s_nop 0
	v_readlane_b32 s6, v44, 0
	v_readlane_b32 s7, v44, 16
	v_readlane_b32 s10, v44, 32
	v_readlane_b32 s11, v44, 48
	s_nop 1
	v_mov_b32_e32 v45, s6
	v_max_f32_e32 v45, s7, v45
	v_max_f32_e32 v45, s10, v45
	v_max_f32_e32 v45, s11, v45
	v_div_scale_f32 v46, s[18:19], v45, v45, s69
	v_rcp_f32_e32 v47, v46
	s_nop 0
	v_fma_f32 v48, -v46, v47, 1.0
	v_fmac_f32_e32 v47, v48, v47
	v_div_scale_f32 v48, vcc, s69, v45, s69
	v_mul_f32_e32 v49, v48, v47
	v_fma_f32 v50, -v46, v49, v48
	v_fmac_f32_e32 v49, v50, v47
	v_fma_f32 v46, -v46, v49, v48
	v_div_fmas_f32 v46, v46, v47, v49
	v_div_fixup_f32 v46, v46, v45, s69
	v_cmp_lt_f32_e32 vcc, 0, v45
	v_mul_f32_e32 v52, 0x3c010204, v45
	v_mov_b32_e32 v84, 0
	v_cndmask_b32_e32 v46, 0, v46, vcc
	v_mul_f32_e32 v40, v46, v40
	v_mul_f32_e32 v41, v46, v41
	v_mul_f32_e32 v42, v46, v42
	v_mul_f32_e32 v43, v46, v43
	v_rndne_f32_e32 v40, v40
	v_rndne_f32_e32 v41, v41
	v_rndne_f32_e32 v42, v42
	v_rndne_f32_e32 v43, v43
	v_cvt_i32_f32_e32 v40, v40
	v_cvt_i32_f32_e32 v41, v41
	v_cvt_i32_f32_e32 v42, v42
	v_cvt_i32_f32_e32 v43, v43
	v_and_b32_e32 v40, 0xff, v40
	v_and_b32_e32 v41, 0xff, v41
	v_and_b32_e32 v42, 0xff, v42
	v_lshl_or_b32 v40, v41, 8, v40
	v_lshl_or_b32 v40, v42, 16, v40
	v_lshl_or_b32 v40, v43, 24, v40
	ds_write_b32 v3, v40
	ds_read_b128 v[32:35], v4
	ds_read_b128 v[36:39], v4 offset:16
	s_waitcnt lgkmcnt(0)
	v_dot4c_i32_i8_e32 v84, 0x1010101, v32
	v_dot4c_i32_i8_e32 v84, 0x1010101, v34
	v_dot4c_i32_i8_e32 v84, 0x1010101, v36
	v_dot4c_i32_i8_e32 v84, 0x1010101, v38
	v_and_b32_e32 v56, s21, v106
	v_and_b32_e32 v57, s23, v106
	v_and_b32_e32 v58, s21, v110
	v_and_b32_e32 v59, s23, v110
	v_and_b32_e32 v60, s21, v114
	v_and_b32_e32 v61, s23, v114
	v_and_b32_e32 v62, s21, v118
	v_and_b32_e32 v63, s23, v118
	v_mul_i32_i24_e32 v85, -8, v84
	v_mov_b32_e32 v64, v85
	v_mov_b32_e32 v86, 0
	v_mov_b32_e32 v65, v85
	v_mov_b32_e32 v87, 0
	v_mov_b32_e32 v66, v85
	v_mov_b32_e32 v88, 0
	v_mov_b32_e32 v67, v85
	v_mov_b32_e32 v89, 0
	v_dot4c_i32_i8_e32 v64, v56, v32
	v_dot4c_i32_i8_e32 v86, v57, v33
	v_dot4c_i32_i8_e32 v65, v58, v32
	v_dot4c_i32_i8_e32 v87, v59, v33
	v_dot4c_i32_i8_e32 v66, v60, v32
	v_dot4c_i32_i8_e32 v88, v61, v33
	v_dot4c_i32_i8_e32 v67, v62, v32
	v_dot4c_i32_i8_e32 v89, v63, v33
	v_and_b32_e32 v56, s21, v107
	v_and_b32_e32 v57, s23, v107
	v_and_b32_e32 v58, s21, v111
	v_and_b32_e32 v59, s23, v111
	v_and_b32_e32 v60, s21, v115
	v_and_b32_e32 v61, s23, v115
	v_and_b32_e32 v62, s21, v119
	v_and_b32_e32 v63, s23, v119
	v_dot4c_i32_i8_e32 v64, v56, v34
	v_dot4c_i32_i8_e32 v86, v57, v35
	v_dot4c_i32_i8_e32 v65, v58, v34
	v_dot4c_i32_i8_e32 v87, v59, v35
	v_dot4c_i32_i8_e32 v66, v60, v34
	v_dot4c_i32_i8_e32 v88, v61, v35
	v_dot4c_i32_i8_e32 v67, v62, v34
	v_dot4c_i32_i8_e32 v89, v63, v35
	v_and_b32_e32 v56, s21, v108
	v_and_b32_e32 v57, s23, v108
	v_and_b32_e32 v58, s21, v112
	v_and_b32_e32 v59, s23, v112
	v_and_b32_e32 v60, s21, v116
	v_and_b32_e32 v61, s23, v116
	v_and_b32_e32 v62, s21, v120
	v_and_b32_e32 v63, s23, v120
	v_dot4c_i32_i8_e32 v64, v56, v36
	v_dot4c_i32_i8_e32 v86, v57, v37
	v_dot4c_i32_i8_e32 v65, v58, v36
	v_dot4c_i32_i8_e32 v87, v59, v37
	v_dot4c_i32_i8_e32 v66, v60, v36
	v_dot4c_i32_i8_e32 v88, v61, v37
	v_dot4c_i32_i8_e32 v67, v62, v36
	v_dot4c_i32_i8_e32 v89, v63, v37
	v_and_b32_e32 v56, s21, v109
	v_and_b32_e32 v57, s23, v109
	v_and_b32_e32 v58, s21, v113
	v_and_b32_e32 v59, s23, v113
	v_and_b32_e32 v60, s21, v117
	v_and_b32_e32 v61, s23, v117
	v_and_b32_e32 v62, s21, v121
	v_and_b32_e32 v63, s23, v121
	v_dot4c_i32_i8_e32 v64, v56, v38
	v_dot4c_i32_i8_e32 v86, v57, v39
	v_dot4c_i32_i8_e32 v65, v58, v38
	v_dot4c_i32_i8_e32 v87, v59, v39
	v_dot4c_i32_i8_e32 v66, v60, v38
	v_dot4c_i32_i8_e32 v88, v61, v39
	v_dot4c_i32_i8_e32 v67, v62, v38
	v_dot4c_i32_i8_e32 v89, v63, v39
	v_ashrrev_i32_e32 v86, 4, v86
	v_ashrrev_i32_e32 v87, 4, v87
	v_ashrrev_i32_e32 v88, 4, v88
	v_ashrrev_i32_e32 v89, 4, v89
	v_add_u32_e32 v64, v64, v86
	v_add_u32_e32 v65, v65, v87
	v_add_u32_e32 v66, v66, v88
	v_add_u32_e32 v67, v67, v89
	v_add_u32_dpp v64, v64, v64 quad_perm:[1,0,3,2] row_mask:0xf bank_mask:0xf bound_ctrl:1
	v_add_u32_dpp v65, v65, v65 quad_perm:[1,0,3,2] row_mask:0xf bank_mask:0xf bound_ctrl:1
	v_add_u32_dpp v66, v66, v66 quad_perm:[1,0,3,2] row_mask:0xf bank_mask:0xf bound_ctrl:1
	v_add_u32_dpp v67, v67, v67 quad_perm:[1,0,3,2] row_mask:0xf bank_mask:0xf bound_ctrl:1
	v_add_u32_dpp v64, v64, v64 quad_perm:[2,3,0,1] row_mask:0xf bank_mask:0xf bound_ctrl:1
	v_add_u32_dpp v65, v65, v65 quad_perm:[2,3,0,1] row_mask:0xf bank_mask:0xf bound_ctrl:1
	v_add_u32_dpp v66, v66, v66 quad_perm:[2,3,0,1] row_mask:0xf bank_mask:0xf bound_ctrl:1
	v_add_u32_dpp v67, v67, v67 quad_perm:[2,3,0,1] row_mask:0xf bank_mask:0xf bound_ctrl:1
	v_add_u32_dpp v64, v64, v64 row_half_mirror row_mask:0xf bank_mask:0xf bound_ctrl:1
	v_add_u32_dpp v65, v65, v65 row_half_mirror row_mask:0xf bank_mask:0xf bound_ctrl:1
	v_add_u32_dpp v66, v66, v66 row_half_mirror row_mask:0xf bank_mask:0xf bound_ctrl:1
; __device__ __forceinline__ void phase_peer_u(const Params& p, int layer, int xs, int wid0, int wstride, char* smraw) {
;     ...
;     float pr[16];
; #pragma unroll
;     for (int i = 0; i < 16; ++i) {
;       int a = 0;
; #pragma unroll
;       for (int m = 0; m < 4; ++m) {
;         const unsigned dw = q[i][m];
;         a = __builtin_amdgcn_sdot4((int)(dw & 0x0f0f0f0fu), xq[2 * m], a, false);
;         a = __builtin_amdgcn_sdot4((int)((dw >> 4) & 0x0f0f0f0fu), xq[2 * m + 1], a, false);
;       }
;       a -= corr;
;       a += __builtin_amdgcn_update_dpp(0, a, 0xB1, 0xF, 0xF, true);
;       a += __builtin_amdgcn_update_dpp(0, a, 0x4E, 0xF, 0xF, true);
;       a += __builtin_amdgcn_update_dpp(0, a, 0x141, 0xF, 0xF, true);
;       pr[i] = (float)a * sx;
;     }
	v_add_u32_dpp v67, v67, v67 row_half_mirror row_mask:0xf bank_mask:0xf bound_ctrl:1
	v_cvt_f32_i32_e32 v68, v64
	v_cvt_f32_i32_e32 v69, v65
	v_cvt_f32_i32_e32 v70, v66
	v_cvt_f32_i32_e32 v71, v67
	v_pk_mul_f32 v[68:69], v[52:53], v[68:69] op_sel_hi:[0,1]
	v_pk_mul_f32 v[70:71], v[52:53], v[70:71] op_sel_hi:[0,1]
	v_and_b32_e32 v56, s21, v122
	v_and_b32_e32 v57, s23, v122
	v_and_b32_e32 v58, s21, v126
	v_and_b32_e32 v59, s23, v126
	v_and_b32_e32 v60, s21, v130
	v_and_b32_e32 v61, s23, v130
	v_and_b32_e32 v62, s21, v134
	v_and_b32_e32 v63, s23, v134
	v_mov_b32_e32 v64, v85
	v_mov_b32_e32 v86, 0
	v_mov_b32_e32 v65, v85
	v_mov_b32_e32 v87, 0
	v_mov_b32_e32 v66, v85
	v_mov_b32_e32 v88, 0
	v_mov_b32_e32 v67, v85
	v_mov_b32_e32 v89, 0
	v_dot4c_i32_i8_e32 v64, v56, v32
	v_dot4c_i32_i8_e32 v86, v57, v33
	v_dot4c_i32_i8_e32 v65, v58, v32
	v_dot4c_i32_i8_e32 v87, v59, v33
	v_dot4c_i32_i8_e32 v66, v60, v32
	v_dot4c_i32_i8_e32 v88, v61, v33
	v_dot4c_i32_i8_e32 v67, v62, v32
	v_dot4c_i32_i8_e32 v89, v63, v33
	v_and_b32_e32 v56, s21, v123
	v_and_b32_e32 v57, s23, v123
	v_and_b32_e32 v58, s21, v127
	v_and_b32_e32 v59, s23, v127
	v_and_b32_e32 v60, s21, v131
	v_and_b32_e32 v61, s23, v131
	v_and_b32_e32 v62, s21, v135
	v_and_b32_e32 v63, s23, v135
	v_dot4c_i32_i8_e32 v64, v56, v34
	v_dot4c_i32_i8_e32 v86, v57, v35
	v_dot4c_i32_i8_e32 v65, v58, v34
	v_dot4c_i32_i8_e32 v87, v59, v35
	v_dot4c_i32_i8_e32 v66, v60, v34
	v_dot4c_i32_i8_e32 v88, v61, v35
	v_dot4c_i32_i8_e32 v67, v62, v34
	v_dot4c_i32_i8_e32 v89, v63, v35
	v_and_b32_e32 v56, s21, v124
	v_and_b32_e32 v57, s23, v124
	v_and_b32_e32 v58, s21, v128
	v_and_b32_e32 v59, s23, v128
	v_and_b32_e32 v60, s21, v132
	v_and_b32_e32 v61, s23, v132
	v_and_b32_e32 v62, s21, v136
	v_and_b32_e32 v63, s23, v136
	v_dot4c_i32_i8_e32 v64, v56, v36
	v_dot4c_i32_i8_e32 v86, v57, v37
	v_dot4c_i32_i8_e32 v65, v58, v36
	v_dot4c_i32_i8_e32 v87, v59, v37
	v_dot4c_i32_i8_e32 v66, v60, v36
	v_dot4c_i32_i8_e32 v88, v61, v37
	v_dot4c_i32_i8_e32 v67, v62, v36
	v_dot4c_i32_i8_e32 v89, v63, v37
	v_and_b32_e32 v56, s21, v125
	v_and_b32_e32 v57, s23, v125
	v_and_b32_e32 v58, s21, v129
	v_and_b32_e32 v59, s23, v129
	v_and_b32_e32 v60, s21, v133
	v_and_b32_e32 v61, s23, v133
	v_and_b32_e32 v62, s21, v137
	v_and_b32_e32 v63, s23, v137
	v_dot4c_i32_i8_e32 v64, v56, v38
	v_dot4c_i32_i8_e32 v86, v57, v39
	v_dot4c_i32_i8_e32 v65, v58, v38
	v_dot4c_i32_i8_e32 v87, v59, v39
	v_dot4c_i32_i8_e32 v66, v60, v38
	v_dot4c_i32_i8_e32 v88, v61, v39
	v_dot4c_i32_i8_e32 v67, v62, v38
	v_dot4c_i32_i8_e32 v89, v63, v39
	v_ashrrev_i32_e32 v86, 4, v86
	v_ashrrev_i32_e32 v87, 4, v87
	v_ashrrev_i32_e32 v88, 4, v88
	v_ashrrev_i32_e32 v89, 4, v89
	v_add_u32_e32 v64, v64, v86
	v_add_u32_e32 v65, v65, v87
	v_add_u32_e32 v66, v66, v88
	v_add_u32_e32 v67, v67, v89
	v_add_u32_dpp v64, v64, v64 quad_perm:[1,0,3,2] row_mask:0xf bank_mask:0xf bound_ctrl:1
	v_add_u32_dpp v65, v65, v65 quad_perm:[1,0,3,2] row_mask:0xf bank_mask:0xf bound_ctrl:1
	v_add_u32_dpp v66, v66, v66 quad_perm:[1,0,3,2] row_mask:0xf bank_mask:0xf bound_ctrl:1
	v_add_u32_dpp v67, v67, v67 quad_perm:[1,0,3,2] row_mask:0xf bank_mask:0xf bound_ctrl:1
	v_add_u32_dpp v64, v64, v64 quad_perm:[2,3,0,1] row_mask:0xf bank_mask:0xf bound_ctrl:1
	v_add_u32_dpp v65, v65, v65 quad_perm:[2,3,0,1] row_mask:0xf bank_mask:0xf bound_ctrl:1
	v_add_u32_dpp v66, v66, v66 quad_perm:[2,3,0,1] row_mask:0xf bank_mask:0xf bound_ctrl:1
	v_add_u32_dpp v67, v67, v67 quad_perm:[2,3,0,1] row_mask:0xf bank_mask:0xf bound_ctrl:1
	v_add_u32_dpp v64, v64, v64 row_half_mirror row_mask:0xf bank_mask:0xf bound_ctrl:1
	v_add_u32_dpp v65, v65, v65 row_half_mirror row_mask:0xf bank_mask:0xf bound_ctrl:1
	v_add_u32_dpp v66, v66, v66 row_half_mirror row_mask:0xf bank_mask:0xf bound_ctrl:1
	v_add_u32_dpp v67, v67, v67 row_half_mirror row_mask:0xf bank_mask:0xf bound_ctrl:1
	v_cvt_f32_i32_e32 v72, v64
	v_cvt_f32_i32_e32 v73, v65
	v_cvt_f32_i32_e32 v74, v66
	v_cvt_f32_i32_e32 v75, v67
	v_pk_mul_f32 v[72:73], v[52:53], v[72:73] op_sel_hi:[0,1]
	v_pk_mul_f32 v[74:75], v[52:53], v[74:75] op_sel_hi:[0,1]
	v_and_b32_e32 v56, s21, v138
	v_and_b32_e32 v57, s23, v138
	v_and_b32_e32 v58, s21, v142
	v_and_b32_e32 v59, s23, v142
	v_and_b32_e32 v60, s21, v146
	v_and_b32_e32 v61, s23, v146
	v_and_b32_e32 v62, s21, v150
	v_and_b32_e32 v63, s23, v150
	v_mov_b32_e32 v64, v85
	v_mov_b32_e32 v86, 0
	v_mov_b32_e32 v65, v85
	v_mov_b32_e32 v87, 0
	v_mov_b32_e32 v66, v85
	v_mov_b32_e32 v88, 0
	v_mov_b32_e32 v67, v85
	v_mov_b32_e32 v89, 0
	v_dot4c_i32_i8_e32 v64, v56, v32
	v_dot4c_i32_i8_e32 v86, v57, v33
	v_dot4c_i32_i8_e32 v65, v58, v32
	v_dot4c_i32_i8_e32 v87, v59, v33
	v_dot4c_i32_i8_e32 v66, v60, v32
	v_dot4c_i32_i8_e32 v88, v61, v33
	v_dot4c_i32_i8_e32 v67, v62, v32
	v_dot4c_i32_i8_e32 v89, v63, v33
	v_and_b32_e32 v56, s21, v139
	v_and_b32_e32 v57, s23, v139
	v_and_b32_e32 v58, s21, v143
	v_and_b32_e32 v59, s23, v143
	v_and_b32_e32 v60, s21, v147
	v_and_b32_e32 v61, s23, v147
	v_and_b32_e32 v62, s21, v151
	v_and_b32_e32 v63, s23, v151
	v_dot4c_i32_i8_e32 v64, v56, v34
	v_dot4c_i32_i8_e32 v86, v57, v35
	v_dot4c_i32_i8_e32 v65, v58, v34
	v_dot4c_i32_i8_e32 v87, v59, v35
	v_dot4c_i32_i8_e32 v66, v60, v34
	v_dot4c_i32_i8_e32 v88, v61, v35
	v_dot4c_i32_i8_e32 v67, v62, v34
	v_dot4c_i32_i8_e32 v89, v63, v35
	v_and_b32_e32 v56, s21, v140
	v_and_b32_e32 v57, s23, v140
	v_and_b32_e32 v58, s21, v144
	v_and_b32_e32 v59, s23, v144
	v_and_b32_e32 v60, s21, v148
	v_and_b32_e32 v61, s23, v148
	v_and_b32_e32 v62, s21, v152
	v_and_b32_e32 v63, s23, v152
	v_dot4c_i32_i8_e32 v64, v56, v36
	v_dot4c_i32_i8_e32 v86, v57, v37
	v_dot4c_i32_i8_e32 v65, v58, v36
	v_dot4c_i32_i8_e32 v87, v59, v37
; __device__ __forceinline__ void phase_peer_u(const Params& p, int layer, int xs, int wid0, int wstride, char* smraw) {
;     ...
;     float pr[16];
; #pragma unroll
;     for (int i = 0; i < 16; ++i) {
;       int a = 0;
; #pragma unroll
;       for (int m = 0; m < 4; ++m) {
;         const unsigned dw = q[i][m];
;         a = __builtin_amdgcn_sdot4((int)(dw & 0x0f0f0f0fu), xq[2 * m], a, false);
;         a = __builtin_amdgcn_sdot4((int)((dw >> 4) & 0x0f0f0f0fu), xq[2 * m + 1], a, false);
;       }
;       a -= corr;
;       a += __builtin_amdgcn_update_dpp(0, a, 0xB1, 0xF, 0xF, true);
;       a += __builtin_amdgcn_update_dpp(0, a, 0x4E, 0xF, 0xF, true);
;       a += __builtin_amdgcn_update_dpp(0, a, 0x141, 0xF, 0xF, true);
;       pr[i] = (float)a * sx;
;     }
;     if (j == 0) {
;       f32x4* dst = (f32x4*)((char*)p.actp + ((unsigned)t * 4096u + (unsigned)(sl * 512 + g * 64)));
; #pragma unroll
;       for (int q4 = 0; q4 < 4; ++q4) dst[q4] = f32x4{pr[q4 * 4], pr[q4 * 4 + 1], pr[q4 * 4 + 2], pr[q4 * 4 + 3]};
;     }
	v_dot4c_i32_i8_e32 v66, v60, v36
	v_dot4c_i32_i8_e32 v88, v61, v37
	v_dot4c_i32_i8_e32 v67, v62, v36
	v_dot4c_i32_i8_e32 v89, v63, v37
	v_and_b32_e32 v56, s21, v141
	v_and_b32_e32 v57, s23, v141
	v_and_b32_e32 v58, s21, v145
	v_and_b32_e32 v59, s23, v145
	v_and_b32_e32 v60, s21, v149
	v_and_b32_e32 v61, s23, v149
	v_and_b32_e32 v62, s21, v153
	v_and_b32_e32 v63, s23, v153
	v_dot4c_i32_i8_e32 v64, v56, v38
	v_dot4c_i32_i8_e32 v86, v57, v39
	v_dot4c_i32_i8_e32 v65, v58, v38
	v_dot4c_i32_i8_e32 v87, v59, v39
	v_dot4c_i32_i8_e32 v66, v60, v38
	v_dot4c_i32_i8_e32 v88, v61, v39
	v_dot4c_i32_i8_e32 v67, v62, v38
	v_dot4c_i32_i8_e32 v89, v63, v39
	v_ashrrev_i32_e32 v86, 4, v86
	v_ashrrev_i32_e32 v87, 4, v87
	v_ashrrev_i32_e32 v88, 4, v88
	v_ashrrev_i32_e32 v89, 4, v89
	v_add_u32_e32 v64, v64, v86
	v_add_u32_e32 v65, v65, v87
	v_add_u32_e32 v66, v66, v88
	v_add_u32_e32 v67, v67, v89
	v_add_u32_dpp v64, v64, v64 quad_perm:[1,0,3,2] row_mask:0xf bank_mask:0xf bound_ctrl:1
	v_add_u32_dpp v65, v65, v65 quad_perm:[1,0,3,2] row_mask:0xf bank_mask:0xf bound_ctrl:1
	v_add_u32_dpp v66, v66, v66 quad_perm:[1,0,3,2] row_mask:0xf bank_mask:0xf bound_ctrl:1
	v_add_u32_dpp v67, v67, v67 quad_perm:[1,0,3,2] row_mask:0xf bank_mask:0xf bound_ctrl:1
	v_add_u32_dpp v64, v64, v64 quad_perm:[2,3,0,1] row_mask:0xf bank_mask:0xf bound_ctrl:1
	v_add_u32_dpp v65, v65, v65 quad_perm:[2,3,0,1] row_mask:0xf bank_mask:0xf bound_ctrl:1
	v_add_u32_dpp v66, v66, v66 quad_perm:[2,3,0,1] row_mask:0xf bank_mask:0xf bound_ctrl:1
	v_add_u32_dpp v67, v67, v67 quad_perm:[2,3,0,1] row_mask:0xf bank_mask:0xf bound_ctrl:1
	v_add_u32_dpp v64, v64, v64 row_half_mirror row_mask:0xf bank_mask:0xf bound_ctrl:1
	v_add_u32_dpp v65, v65, v65 row_half_mirror row_mask:0xf bank_mask:0xf bound_ctrl:1
	v_add_u32_dpp v66, v66, v66 row_half_mirror row_mask:0xf bank_mask:0xf bound_ctrl:1
	v_add_u32_dpp v67, v67, v67 row_half_mirror row_mask:0xf bank_mask:0xf bound_ctrl:1
	v_cvt_f32_i32_e32 v76, v64
	v_cvt_f32_i32_e32 v77, v65
	v_cvt_f32_i32_e32 v78, v66
	v_cvt_f32_i32_e32 v79, v67
	v_pk_mul_f32 v[76:77], v[52:53], v[76:77] op_sel_hi:[0,1]
	v_pk_mul_f32 v[78:79], v[52:53], v[78:79] op_sel_hi:[0,1]
	v_and_b32_e32 v56, s21, v154
	v_and_b32_e32 v57, s23, v154
	v_and_b32_e32 v58, s21, v158
	v_and_b32_e32 v59, s23, v158
	v_and_b32_e32 v60, s21, v162
	v_and_b32_e32 v61, s23, v162
	v_and_b32_e32 v62, s21, v166
	v_and_b32_e32 v63, s23, v166
	v_mov_b32_e32 v64, v85
	v_mov_b32_e32 v86, 0
	v_mov_b32_e32 v65, v85
	v_mov_b32_e32 v87, 0
	v_mov_b32_e32 v66, v85
	v_mov_b32_e32 v88, 0
	v_mov_b32_e32 v67, v85
	v_mov_b32_e32 v89, 0
	v_dot4c_i32_i8_e32 v64, v56, v32
	v_dot4c_i32_i8_e32 v86, v57, v33
	v_dot4c_i32_i8_e32 v65, v58, v32
	v_dot4c_i32_i8_e32 v87, v59, v33
	v_dot4c_i32_i8_e32 v66, v60, v32
	v_dot4c_i32_i8_e32 v88, v61, v33
	v_dot4c_i32_i8_e32 v67, v62, v32
	v_dot4c_i32_i8_e32 v89, v63, v33
	v_and_b32_e32 v56, s21, v155
	v_and_b32_e32 v57, s23, v155
	v_and_b32_e32 v58, s21, v159
	v_and_b32_e32 v59, s23, v159
	v_and_b32_e32 v60, s21, v163
	v_and_b32_e32 v61, s23, v163
	v_and_b32_e32 v62, s21, v167
	v_and_b32_e32 v63, s23, v167
	v_dot4c_i32_i8_e32 v64, v56, v34
	v_dot4c_i32_i8_e32 v86, v57, v35
	v_dot4c_i32_i8_e32 v65, v58, v34
	v_dot4c_i32_i8_e32 v87, v59, v35
	v_dot4c_i32_i8_e32 v66, v60, v34
	v_dot4c_i32_i8_e32 v88, v61, v35
	v_dot4c_i32_i8_e32 v67, v62, v34
	v_dot4c_i32_i8_e32 v89, v63, v35
	v_and_b32_e32 v56, s21, v156
	v_and_b32_e32 v57, s23, v156
	v_and_b32_e32 v58, s21, v160
	v_and_b32_e32 v59, s23, v160
	v_and_b32_e32 v60, s21, v164
	v_and_b32_e32 v61, s23, v164
	v_and_b32_e32 v62, s21, v168
	v_and_b32_e32 v63, s23, v168
	v_dot4c_i32_i8_e32 v64, v56, v36
	v_dot4c_i32_i8_e32 v86, v57, v37
	v_dot4c_i32_i8_e32 v65, v58, v36
	v_dot4c_i32_i8_e32 v87, v59, v37
	v_dot4c_i32_i8_e32 v66, v60, v36
	v_dot4c_i32_i8_e32 v88, v61, v37
	v_dot4c_i32_i8_e32 v67, v62, v36
	v_dot4c_i32_i8_e32 v89, v63, v37
	v_and_b32_e32 v56, s21, v157
	v_and_b32_e32 v57, s23, v157
	v_and_b32_e32 v58, s21, v161
	v_and_b32_e32 v59, s23, v161
	v_and_b32_e32 v60, s21, v165
	v_and_b32_e32 v61, s23, v165
	v_and_b32_e32 v62, s21, v169
	v_and_b32_e32 v63, s23, v169
	v_dot4c_i32_i8_e32 v64, v56, v38
	v_dot4c_i32_i8_e32 v86, v57, v39
	v_dot4c_i32_i8_e32 v65, v58, v38
	v_dot4c_i32_i8_e32 v87, v59, v39
	v_dot4c_i32_i8_e32 v66, v60, v38
	v_dot4c_i32_i8_e32 v88, v61, v39
	v_dot4c_i32_i8_e32 v67, v62, v38
	v_dot4c_i32_i8_e32 v89, v63, v39
	v_ashrrev_i32_e32 v86, 4, v86
	v_ashrrev_i32_e32 v87, 4, v87
	v_ashrrev_i32_e32 v88, 4, v88
	v_ashrrev_i32_e32 v89, 4, v89
	v_add_u32_e32 v64, v64, v86
	v_add_u32_e32 v65, v65, v87
	v_add_u32_e32 v66, v66, v88
	v_add_u32_e32 v67, v67, v89
	v_add_u32_dpp v64, v64, v64 quad_perm:[1,0,3,2] row_mask:0xf bank_mask:0xf bound_ctrl:1
	v_add_u32_dpp v65, v65, v65 quad_perm:[1,0,3,2] row_mask:0xf bank_mask:0xf bound_ctrl:1
	v_add_u32_dpp v66, v66, v66 quad_perm:[1,0,3,2] row_mask:0xf bank_mask:0xf bound_ctrl:1
	v_add_u32_dpp v67, v67, v67 quad_perm:[1,0,3,2] row_mask:0xf bank_mask:0xf bound_ctrl:1
	v_add_u32_dpp v64, v64, v64 quad_perm:[2,3,0,1] row_mask:0xf bank_mask:0xf bound_ctrl:1
	v_add_u32_dpp v65, v65, v65 quad_perm:[2,3,0,1] row_mask:0xf bank_mask:0xf bound_ctrl:1
	v_add_u32_dpp v66, v66, v66 quad_perm:[2,3,0,1] row_mask:0xf bank_mask:0xf bound_ctrl:1
	v_add_u32_dpp v67, v67, v67 quad_perm:[2,3,0,1] row_mask:0xf bank_mask:0xf bound_ctrl:1
	v_add_u32_dpp v64, v64, v64 row_half_mirror row_mask:0xf bank_mask:0xf bound_ctrl:1
	v_add_u32_dpp v65, v65, v65 row_half_mirror row_mask:0xf bank_mask:0xf bound_ctrl:1
	v_add_u32_dpp v66, v66, v66 row_half_mirror row_mask:0xf bank_mask:0xf bound_ctrl:1
	v_add_u32_dpp v67, v67, v67 row_half_mirror row_mask:0xf bank_mask:0xf bound_ctrl:1
	v_cvt_f32_i32_e32 v80, v64
	v_cvt_f32_i32_e32 v81, v65
	v_cvt_f32_i32_e32 v82, v66
	v_cvt_f32_i32_e32 v83, v67
	v_pk_mul_f32 v[80:81], v[52:53], v[80:81] op_sel_hi:[0,1]
	v_pk_mul_f32 v[82:83], v[52:53], v[82:83] op_sel_hi:[0,1]
	s_lshl_b32 s70, s60, 1
	s_add_u32 s70, s70, s28
	s_lshl_b32 s70, s70, 12
	s_add_u32 s70, s70, s68
	s_mov_b64 s[74:75], exec
	s_and_b64 exec, exec, s[72:73]
	v_add_u32_e32 v9, s70, v5
	global_store_dwordx4 v9, v[68:71], s[64:65]
	global_store_dwordx4 v9, v[72:75], s[64:65] offset:16
	global_store_dwordx4 v9, v[76:79], s[64:65] offset:32
	global_store_dwordx4 v9, v[80:83], s[64:65] offset:48
	s_mov_b64 exec, s[74:75]
	s_mov_b32 s60, s62
	s_cmp_lt_u32 s60, s61
	s_cbranch_scc0 .Lmy_pu0_done

; __device__ __forceinline__ float bflo(unsigned u) { return __uint_as_float(u << 16); }
; __device__ __forceinline__ float bfhi(unsigned u) { return __uint_as_float(u & 0xffff0000u); }
; __device__ __forceinline__ void phase_peer_u(const Params& p, int layer, int xs, int wid0, int wstride, char* smraw) {
;     ...
;     int xq[8]; float sx; int sumx = 0;
;     {
;       const float x0 = bflo(xv[0]), x1 = bfhi(xv[0]), x2 = bflo(xv[1]), x3 = bfhi(xv[1]);
;       float mx = fmaxf(fmaxf(fabsf(x0), fabsf(x1)), fmaxf(fabsf(x2), fabsf(x3)));
; #pragma unroll
;       for (int m = 32; m >= 1; m >>= 1) mx = fmaxf(mx, __shfl_xor(mx, m));
;       const float inv = mx > 0.f ? 127.f / mx : 0.f;
;       sx = mx * (1.f / 127.f);
;       const int q0 = __float2int_rn(x0 * inv), q1 = __float2int_rn(x1 * inv), q2 = __float2int_rn(x2 * inv), q3 = __float2int_rn(x3 * inv);
;       asm volatile("" ::: "memory");
;       *(int*)(xqs + l * 4) = (q0 & 0xff) | ((q1 & 0xff) << 8) | ((q2 & 0xff) << 16) | ((q3 & 0xff) << 24);
;       asm volatile("" ::: "memory");
;       __builtin_amdgcn_wave_barrier();
;       asm volatile("" ::: "memory");
;       const u32x4 xa = *(const u32x4*)(xqs + j * 32), xb = *(const u32x4*)(xqs + j * 32 + 16);
;       asm volatile("" ::: "memory");
; #pragma unroll
;       for (int m = 0; m < 4; ++m) { xq[m] = (int)xa[m]; xq[4 + m] = (int)xb[m]; }
; #pragma unroll
;       for (int m = 0; m < 8; ++m) sumx = __builtin_amdgcn_sdot4(xq[m], 0x01010101, sumx, false);
;     }
;     const int corr = 8 * sumx;
;     float pr[16];
; #pragma unroll
;     for (int i = 0; i < 16; ++i) {
;       int a = 0;
; #pragma unroll
;       for (int m = 0; m < 4; ++m) {
;         const unsigned dw = q[i][m];
;         a = __builtin_amdgcn_sdot4((int)(dw & 0x0f0f0f0fu), xq[2 * m], a, false);
;         a = __builtin_amdgcn_sdot4((int)((dw >> 4) & 0x0f0f0f0fu), xq[2 * m + 1], a, false);
;       }
;       a -= corr;
;       a += __builtin_amdgcn_update_dpp(0, a, 0xB1, 0xF, 0xF, true);
;       a += __builtin_amdgcn_update_dpp(0, a, 0x4E, 0xF, 0xF, true);
;       a += __builtin_amdgcn_update_dpp(0, a, 0x141, 0xF, 0xF, true);
;       pr[i] = (float)a * sx;
;     }
.Lmy_pu0_noissueB:
	v_lshlrev_b32_e32 v40, 16, v28
	v_and_b32_e32 v41, 0xffff0000, v28
	v_lshlrev_b32_e32 v42, 16, v29
	v_and_b32_e32 v43, 0xffff0000, v29
	v_max_f32_e64 v44, |v40|, |v41|
	v_max3_f32 v44, |v42|, |v43|, v44
	s_nop 1
	v_max_f32_dpp v44, v44, v44 quad_perm:[1,0,3,2] row_mask:0xf bank_mask:0xf bound_ctrl:1
	s_nop 1
	v_max_f32_dpp v44, v44, v44 quad_perm:[2,3,0,1] row_mask:0xf bank_mask:0xf bound_ctrl:1
	s_nop 1
	v_max_f32_dpp v44, v44, v44 row_half_mirror row_mask:0xf bank_mask:0xf bound_ctrl:1
	s_nop 1
	v_max_f32_dpp v44, v44, v44 row_mirror row_mask:0xf bank_mask:0xf bound_ctrl:1
	s_nop 0
	v_readlane_b32 s6, v44, 0
	v_readlane_b32 s7, v44, 16
	v_readlane_b32 s10, v44, 32
	v_readlane_b32 s11, v44, 48
	s_nop 1
	v_mov_b32_e32 v45, s6
	v_max_f32_e32 v45, s7, v45
	v_max_f32_e32 v45, s10, v45
	v_max_f32_e32 v45, s11, v45
	v_div_scale_f32 v46, s[18:19], v45, v45, s69
	v_rcp_f32_e32 v47, v46
	s_nop 0
	v_fma_f32 v48, -v46, v47, 1.0
	v_fmac_f32_e32 v47, v48, v47
	v_div_scale_f32 v48, vcc, s69, v45, s69
	v_mul_f32_e32 v49, v48, v47
	v_fma_f32 v50, -v46, v49, v48
	v_fmac_f32_e32 v49, v50, v47
	v_fma_f32 v46, -v46, v49, v48
	v_div_fmas_f32 v46, v46, v47, v49
	v_div_fixup_f32 v46, v46, v45, s69
	v_cmp_lt_f32_e32 vcc, 0, v45
	v_mul_f32_e32 v52, 0x3c010204, v45
	v_mov_b32_e32 v84, 0
	v_cndmask_b32_e32 v46, 0, v46, vcc
	v_mul_f32_e32 v40, v46, v40
	v_mul_f32_e32 v41, v46, v41
	v_mul_f32_e32 v42, v46, v42
	v_mul_f32_e32 v43, v46, v43
	v_rndne_f32_e32 v40, v40
	v_rndne_f32_e32 v41, v41
	v_rndne_f32_e32 v42, v42
	v_rndne_f32_e32 v43, v43
	v_cvt_i32_f32_e32 v40, v40
	v_cvt_i32_f32_e32 v41, v41
	v_cvt_i32_f32_e32 v42, v42
	v_cvt_i32_f32_e32 v43, v43
	v_and_b32_e32 v40, 0xff, v40
	v_and_b32_e32 v41, 0xff, v41
	v_and_b32_e32 v42, 0xff, v42
	v_lshl_or_b32 v40, v41, 8, v40
	v_lshl_or_b32 v40, v42, 16, v40
	v_lshl_or_b32 v40, v43, 24, v40
	ds_write_b32 v3, v40
	ds_read_b128 v[32:35], v4
	ds_read_b128 v[36:39], v4 offset:16
	s_waitcnt lgkmcnt(0)
	v_dot4c_i32_i8_e32 v84, 0x1010101, v32
	v_dot4c_i32_i8_e32 v84, 0x1010101, v34
	v_dot4c_i32_i8_e32 v84, 0x1010101, v36
	v_dot4c_i32_i8_e32 v84, 0x1010101, v38
	v_and_b32_e32 v56, s21, v170
	v_and_b32_e32 v57, s23, v170
	v_and_b32_e32 v58, s21, v174
	v_and_b32_e32 v59, s23, v174
	v_and_b32_e32 v60, s21, v178
	v_and_b32_e32 v61, s23, v178
	v_and_b32_e32 v62, s21, v182
	v_and_b32_e32 v63, s23, v182
	v_mul_i32_i24_e32 v85, -8, v84
	v_mov_b32_e32 v64, v85
	v_mov_b32_e32 v86, 0
	v_mov_b32_e32 v65, v85
	v_mov_b32_e32 v87, 0
	v_mov_b32_e32 v66, v85
	v_mov_b32_e32 v88, 0
	v_mov_b32_e32 v67, v85
	v_mov_b32_e32 v89, 0
	v_dot4c_i32_i8_e32 v64, v56, v32
	v_dot4c_i32_i8_e32 v86, v57, v33
	v_dot4c_i32_i8_e32 v65, v58, v32
	v_dot4c_i32_i8_e32 v87, v59, v33
	v_dot4c_i32_i8_e32 v66, v60, v32
	v_dot4c_i32_i8_e32 v88, v61, v33
	v_dot4c_i32_i8_e32 v67, v62, v32
	v_dot4c_i32_i8_e32 v89, v63, v33
	v_and_b32_e32 v56, s21, v171
	v_and_b32_e32 v57, s23, v171
	v_and_b32_e32 v58, s21, v175
	v_and_b32_e32 v59, s23, v175
	v_and_b32_e32 v60, s21, v179
	v_and_b32_e32 v61, s23, v179
	v_and_b32_e32 v62, s21, v183
	v_and_b32_e32 v63, s23, v183
	v_dot4c_i32_i8_e32 v64, v56, v34
	v_dot4c_i32_i8_e32 v86, v57, v35
	v_dot4c_i32_i8_e32 v65, v58, v34
	v_dot4c_i32_i8_e32 v87, v59, v35
	v_dot4c_i32_i8_e32 v66, v60, v34
	v_dot4c_i32_i8_e32 v88, v61, v35
	v_dot4c_i32_i8_e32 v67, v62, v34
	v_dot4c_i32_i8_e32 v89, v63, v35
	v_and_b32_e32 v56, s21, v172
	v_and_b32_e32 v57, s23, v172
	v_and_b32_e32 v58, s21, v176
	v_and_b32_e32 v59, s23, v176
	v_and_b32_e32 v60, s21, v180
	v_and_b32_e32 v61, s23, v180
	v_and_b32_e32 v62, s21, v184
	v_and_b32_e32 v63, s23, v184
	v_dot4c_i32_i8_e32 v64, v56, v36
	v_dot4c_i32_i8_e32 v86, v57, v37
	v_dot4c_i32_i8_e32 v65, v58, v36
	v_dot4c_i32_i8_e32 v87, v59, v37
	v_dot4c_i32_i8_e32 v66, v60, v36
	v_dot4c_i32_i8_e32 v88, v61, v37
	v_dot4c_i32_i8_e32 v67, v62, v36
	v_dot4c_i32_i8_e32 v89, v63, v37
	v_and_b32_e32 v56, s21, v173
	v_and_b32_e32 v57, s23, v173
	v_and_b32_e32 v58, s21, v177
	v_and_b32_e32 v59, s23, v177
	v_and_b32_e32 v60, s21, v181
	v_and_b32_e32 v61, s23, v181
	v_and_b32_e32 v62, s21, v185
	v_and_b32_e32 v63, s23, v185
	v_dot4c_i32_i8_e32 v64, v56, v38
	v_dot4c_i32_i8_e32 v86, v57, v39
	v_dot4c_i32_i8_e32 v65, v58, v38
	v_dot4c_i32_i8_e32 v87, v59, v39
	v_dot4c_i32_i8_e32 v66, v60, v38
	v_dot4c_i32_i8_e32 v88, v61, v39
	v_dot4c_i32_i8_e32 v67, v62, v38
	v_dot4c_i32_i8_e32 v89, v63, v39
	v_ashrrev_i32_e32 v86, 4, v86
	v_ashrrev_i32_e32 v87, 4, v87
	v_ashrrev_i32_e32 v88, 4, v88
	v_ashrrev_i32_e32 v89, 4, v89
	v_add_u32_e32 v64, v64, v86
	v_add_u32_e32 v65, v65, v87
	v_add_u32_e32 v66, v66, v88
	v_add_u32_e32 v67, v67, v89
	v_add_u32_dpp v64, v64, v64 quad_perm:[1,0,3,2] row_mask:0xf bank_mask:0xf bound_ctrl:1
	v_add_u32_dpp v65, v65, v65 quad_perm:[1,0,3,2] row_mask:0xf bank_mask:0xf bound_ctrl:1
	v_add_u32_dpp v66, v66, v66 quad_perm:[1,0,3,2] row_mask:0xf bank_mask:0xf bound_ctrl:1
	v_add_u32_dpp v67, v67, v67 quad_perm:[1,0,3,2] row_mask:0xf bank_mask:0xf bound_ctrl:1
	v_add_u32_dpp v64, v64, v64 quad_perm:[2,3,0,1] row_mask:0xf bank_mask:0xf bound_ctrl:1
	v_add_u32_dpp v65, v65, v65 quad_perm:[2,3,0,1] row_mask:0xf bank_mask:0xf bound_ctrl:1
	v_add_u32_dpp v66, v66, v66 quad_perm:[2,3,0,1] row_mask:0xf bank_mask:0xf bound_ctrl:1
	v_add_u32_dpp v67, v67, v67 quad_perm:[2,3,0,1] row_mask:0xf bank_mask:0xf bound_ctrl:1
	v_add_u32_dpp v64, v64, v64 row_half_mirror row_mask:0xf bank_mask:0xf bound_ctrl:1
	v_add_u32_dpp v65, v65, v65 row_half_mirror row_mask:0xf bank_mask:0xf bound_ctrl:1
	v_add_u32_dpp v66, v66, v66 row_half_mirror row_mask:0xf bank_mask:0xf bound_ctrl:1
; __device__ __forceinline__ void phase_peer_u(const Params& p, int layer, int xs, int wid0, int wstride, char* smraw) {
;     ...
;     float pr[16];
; #pragma unroll
;     for (int i = 0; i < 16; ++i) {
;       int a = 0;
; #pragma unroll
;       for (int m = 0; m < 4; ++m) {
;         const unsigned dw = q[i][m];
;         a = __builtin_amdgcn_sdot4((int)(dw & 0x0f0f0f0fu), xq[2 * m], a, false);
;         a = __builtin_amdgcn_sdot4((int)((dw >> 4) & 0x0f0f0f0fu), xq[2 * m + 1], a, false);
;       }
;       a -= corr;
;       a += __builtin_amdgcn_update_dpp(0, a, 0xB1, 0xF, 0xF, true);
;       a += __builtin_amdgcn_update_dpp(0, a, 0x4E, 0xF, 0xF, true);
;       a += __builtin_amdgcn_update_dpp(0, a, 0x141, 0xF, 0xF, true);
;       pr[i] = (float)a * sx;
;     }
	v_add_u32_dpp v67, v67, v67 row_half_mirror row_mask:0xf bank_mask:0xf bound_ctrl:1
	v_cvt_f32_i32_e32 v68, v64
	v_cvt_f32_i32_e32 v69, v65
	v_cvt_f32_i32_e32 v70, v66
	v_cvt_f32_i32_e32 v71, v67
	v_pk_mul_f32 v[68:69], v[52:53], v[68:69] op_sel_hi:[0,1]
	v_pk_mul_f32 v[70:71], v[52:53], v[70:71] op_sel_hi:[0,1]
	v_and_b32_e32 v56, s21, v192
	v_and_b32_e32 v57, s23, v192
	v_and_b32_e32 v58, s21, v196
	v_and_b32_e32 v59, s23, v196
	v_and_b32_e32 v60, s21, v200
	v_and_b32_e32 v61, s23, v200
	v_and_b32_e32 v62, s21, v204
	v_and_b32_e32 v63, s23, v204
	v_mov_b32_e32 v64, v85
	v_mov_b32_e32 v86, 0
	v_mov_b32_e32 v65, v85
	v_mov_b32_e32 v87, 0
	v_mov_b32_e32 v66, v85
	v_mov_b32_e32 v88, 0
	v_mov_b32_e32 v67, v85
	v_mov_b32_e32 v89, 0
	v_dot4c_i32_i8_e32 v64, v56, v32
	v_dot4c_i32_i8_e32 v86, v57, v33
	v_dot4c_i32_i8_e32 v65, v58, v32
	v_dot4c_i32_i8_e32 v87, v59, v33
	v_dot4c_i32_i8_e32 v66, v60, v32
	v_dot4c_i32_i8_e32 v88, v61, v33
	v_dot4c_i32_i8_e32 v67, v62, v32
	v_dot4c_i32_i8_e32 v89, v63, v33
	v_and_b32_e32 v56, s21, v193
	v_and_b32_e32 v57, s23, v193
	v_and_b32_e32 v58, s21, v197
	v_and_b32_e32 v59, s23, v197
	v_and_b32_e32 v60, s21, v201
	v_and_b32_e32 v61, s23, v201
	v_and_b32_e32 v62, s21, v205
	v_and_b32_e32 v63, s23, v205
	v_dot4c_i32_i8_e32 v64, v56, v34
	v_dot4c_i32_i8_e32 v86, v57, v35
	v_dot4c_i32_i8_e32 v65, v58, v34
	v_dot4c_i32_i8_e32 v87, v59, v35
	v_dot4c_i32_i8_e32 v66, v60, v34
	v_dot4c_i32_i8_e32 v88, v61, v35
	v_dot4c_i32_i8_e32 v67, v62, v34
	v_dot4c_i32_i8_e32 v89, v63, v35
	v_and_b32_e32 v56, s21, v194
	v_and_b32_e32 v57, s23, v194
	v_and_b32_e32 v58, s21, v198
	v_and_b32_e32 v59, s23, v198
	v_and_b32_e32 v60, s21, v202
	v_and_b32_e32 v61, s23, v202
	v_and_b32_e32 v62, s21, v206
	v_and_b32_e32 v63, s23, v206
	v_dot4c_i32_i8_e32 v64, v56, v36
	v_dot4c_i32_i8_e32 v86, v57, v37
	v_dot4c_i32_i8_e32 v65, v58, v36
	v_dot4c_i32_i8_e32 v87, v59, v37
	v_dot4c_i32_i8_e32 v66, v60, v36
	v_dot4c_i32_i8_e32 v88, v61, v37
	v_dot4c_i32_i8_e32 v67, v62, v36
	v_dot4c_i32_i8_e32 v89, v63, v37
	v_and_b32_e32 v56, s21, v195
	v_and_b32_e32 v57, s23, v195
	v_and_b32_e32 v58, s21, v199
	v_and_b32_e32 v59, s23, v199
	v_and_b32_e32 v60, s21, v203
	v_and_b32_e32 v61, s23, v203
	v_and_b32_e32 v62, s21, v207
	v_and_b32_e32 v63, s23, v207
	v_dot4c_i32_i8_e32 v64, v56, v38
	v_dot4c_i32_i8_e32 v86, v57, v39
	v_dot4c_i32_i8_e32 v65, v58, v38
	v_dot4c_i32_i8_e32 v87, v59, v39
	v_dot4c_i32_i8_e32 v66, v60, v38
	v_dot4c_i32_i8_e32 v88, v61, v39
	v_dot4c_i32_i8_e32 v67, v62, v38
	v_dot4c_i32_i8_e32 v89, v63, v39
	v_ashrrev_i32_e32 v86, 4, v86
	v_ashrrev_i32_e32 v87, 4, v87
	v_ashrrev_i32_e32 v88, 4, v88
	v_ashrrev_i32_e32 v89, 4, v89
	v_add_u32_e32 v64, v64, v86
	v_add_u32_e32 v65, v65, v87
	v_add_u32_e32 v66, v66, v88
	v_add_u32_e32 v67, v67, v89
	v_add_u32_dpp v64, v64, v64 quad_perm:[1,0,3,2] row_mask:0xf bank_mask:0xf bound_ctrl:1
	v_add_u32_dpp v65, v65, v65 quad_perm:[1,0,3,2] row_mask:0xf bank_mask:0xf bound_ctrl:1
	v_add_u32_dpp v66, v66, v66 quad_perm:[1,0,3,2] row_mask:0xf bank_mask:0xf bound_ctrl:1
	v_add_u32_dpp v67, v67, v67 quad_perm:[1,0,3,2] row_mask:0xf bank_mask:0xf bound_ctrl:1
	v_add_u32_dpp v64, v64, v64 quad_perm:[2,3,0,1] row_mask:0xf bank_mask:0xf bound_ctrl:1
	v_add_u32_dpp v65, v65, v65 quad_perm:[2,3,0,1] row_mask:0xf bank_mask:0xf bound_ctrl:1
	v_add_u32_dpp v66, v66, v66 quad_perm:[2,3,0,1] row_mask:0xf bank_mask:0xf bound_ctrl:1
	v_add_u32_dpp v67, v67, v67 quad_perm:[2,3,0,1] row_mask:0xf bank_mask:0xf bound_ctrl:1
	v_add_u32_dpp v64, v64, v64 row_half_mirror row_mask:0xf bank_mask:0xf bound_ctrl:1
	v_add_u32_dpp v65, v65, v65 row_half_mirror row_mask:0xf bank_mask:0xf bound_ctrl:1
	v_add_u32_dpp v66, v66, v66 row_half_mirror row_mask:0xf bank_mask:0xf bound_ctrl:1
	v_add_u32_dpp v67, v67, v67 row_half_mirror row_mask:0xf bank_mask:0xf bound_ctrl:1
	v_cvt_f32_i32_e32 v72, v64
	v_cvt_f32_i32_e32 v73, v65
	v_cvt_f32_i32_e32 v74, v66
	v_cvt_f32_i32_e32 v75, v67
	v_pk_mul_f32 v[72:73], v[52:53], v[72:73] op_sel_hi:[0,1]
	v_pk_mul_f32 v[74:75], v[52:53], v[74:75] op_sel_hi:[0,1]
	v_and_b32_e32 v56, s21, v208
	v_and_b32_e32 v57, s23, v208
	v_and_b32_e32 v58, s21, v212
	v_and_b32_e32 v59, s23, v212
	v_and_b32_e32 v60, s21, v216
	v_and_b32_e32 v61, s23, v216
	v_and_b32_e32 v62, s21, v220
	v_and_b32_e32 v63, s23, v220
	v_mov_b32_e32 v64, v85
	v_mov_b32_e32 v86, 0
	v_mov_b32_e32 v65, v85
	v_mov_b32_e32 v87, 0
	v_mov_b32_e32 v66, v85
	v_mov_b32_e32 v88, 0
	v_mov_b32_e32 v67, v85
	v_mov_b32_e32 v89, 0
	v_dot4c_i32_i8_e32 v64, v56, v32
	v_dot4c_i32_i8_e32 v86, v57, v33
	v_dot4c_i32_i8_e32 v65, v58, v32
	v_dot4c_i32_i8_e32 v87, v59, v33
	v_dot4c_i32_i8_e32 v66, v60, v32
	v_dot4c_i32_i8_e32 v88, v61, v33
	v_dot4c_i32_i8_e32 v67, v62, v32
	v_dot4c_i32_i8_e32 v89, v63, v33
	v_and_b32_e32 v56, s21, v209
	v_and_b32_e32 v57, s23, v209
	v_and_b32_e32 v58, s21, v213
	v_and_b32_e32 v59, s23, v213
	v_and_b32_e32 v60, s21, v217
	v_and_b32_e32 v61, s23, v217
	v_and_b32_e32 v62, s21, v221
	v_and_b32_e32 v63, s23, v221
	v_dot4c_i32_i8_e32 v64, v56, v34
	v_dot4c_i32_i8_e32 v86, v57, v35
	v_dot4c_i32_i8_e32 v65, v58, v34
	v_dot4c_i32_i8_e32 v87, v59, v35
	v_dot4c_i32_i8_e32 v66, v60, v34
	v_dot4c_i32_i8_e32 v88, v61, v35
	v_dot4c_i32_i8_e32 v67, v62, v34
	v_dot4c_i32_i8_e32 v89, v63, v35
	v_and_b32_e32 v56, s21, v210
	v_and_b32_e32 v57, s23, v210
	v_and_b32_e32 v58, s21, v214
	v_and_b32_e32 v59, s23, v214
	v_and_b32_e32 v60, s21, v218
	v_and_b32_e32 v61, s23, v218
	v_and_b32_e32 v62, s21, v222
	v_and_b32_e32 v63, s23, v222
	v_dot4c_i32_i8_e32 v64, v56, v36
	v_dot4c_i32_i8_e32 v86, v57, v37
	v_dot4c_i32_i8_e32 v65, v58, v36
	v_dot4c_i32_i8_e32 v87, v59, v37
; __device__ __forceinline__ void phase_peer_u(const Params& p, int layer, int xs, int wid0, int wstride, char* smraw) {
;     ...
;     float pr[16];
; #pragma unroll
;     for (int i = 0; i < 16; ++i) {
;       int a = 0;
; #pragma unroll
;       for (int m = 0; m < 4; ++m) {
;         const unsigned dw = q[i][m];
;         a = __builtin_amdgcn_sdot4((int)(dw & 0x0f0f0f0fu), xq[2 * m], a, false);
;         a = __builtin_amdgcn_sdot4((int)((dw >> 4) & 0x0f0f0f0fu), xq[2 * m + 1], a, false);
;       }
;       a -= corr;
;       a += __builtin_amdgcn_update_dpp(0, a, 0xB1, 0xF, 0xF, true);
;       a += __builtin_amdgcn_update_dpp(0, a, 0x4E, 0xF, 0xF, true);
;       a += __builtin_amdgcn_update_dpp(0, a, 0x141, 0xF, 0xF, true);
;       pr[i] = (float)a * sx;
;     }
;     if (j == 0) {
;       f32x4* dst = (f32x4*)((char*)p.actp + ((unsigned)t * 4096u + (unsigned)(sl * 512 + g * 64)));
; #pragma unroll
;       for (int q4 = 0; q4 < 4; ++q4) dst[q4] = f32x4{pr[q4 * 4], pr[q4 * 4 + 1], pr[q4 * 4 + 2], pr[q4 * 4 + 3]};
;     }
;     ...
;     compute(tt, qB, xB);
;     tt += wstride;
;   }
	v_dot4c_i32_i8_e32 v66, v60, v36
	v_dot4c_i32_i8_e32 v88, v61, v37
	v_dot4c_i32_i8_e32 v67, v62, v36
	v_dot4c_i32_i8_e32 v89, v63, v37
	v_and_b32_e32 v56, s21, v211
	v_and_b32_e32 v57, s23, v211
	v_and_b32_e32 v58, s21, v215
	v_and_b32_e32 v59, s23, v215
	v_and_b32_e32 v60, s21, v219
	v_and_b32_e32 v61, s23, v219
	v_and_b32_e32 v62, s21, v223
	v_and_b32_e32 v63, s23, v223
	v_dot4c_i32_i8_e32 v64, v56, v38
	v_dot4c_i32_i8_e32 v86, v57, v39
	v_dot4c_i32_i8_e32 v65, v58, v38
	v_dot4c_i32_i8_e32 v87, v59, v39
	v_dot4c_i32_i8_e32 v66, v60, v38
	v_dot4c_i32_i8_e32 v88, v61, v39
	v_dot4c_i32_i8_e32 v67, v62, v38
	v_dot4c_i32_i8_e32 v89, v63, v39
	v_ashrrev_i32_e32 v86, 4, v86
	v_ashrrev_i32_e32 v87, 4, v87
	v_ashrrev_i32_e32 v88, 4, v88
	v_ashrrev_i32_e32 v89, 4, v89
	v_add_u32_e32 v64, v64, v86
	v_add_u32_e32 v65, v65, v87
	v_add_u32_e32 v66, v66, v88
	v_add_u32_e32 v67, v67, v89
	v_add_u32_dpp v64, v64, v64 quad_perm:[1,0,3,2] row_mask:0xf bank_mask:0xf bound_ctrl:1
	v_add_u32_dpp v65, v65, v65 quad_perm:[1,0,3,2] row_mask:0xf bank_mask:0xf bound_ctrl:1
	v_add_u32_dpp v66, v66, v66 quad_perm:[1,0,3,2] row_mask:0xf bank_mask:0xf bound_ctrl:1
	v_add_u32_dpp v67, v67, v67 quad_perm:[1,0,3,2] row_mask:0xf bank_mask:0xf bound_ctrl:1
	v_add_u32_dpp v64, v64, v64 quad_perm:[2,3,0,1] row_mask:0xf bank_mask:0xf bound_ctrl:1
	v_add_u32_dpp v65, v65, v65 quad_perm:[2,3,0,1] row_mask:0xf bank_mask:0xf bound_ctrl:1
	v_add_u32_dpp v66, v66, v66 quad_perm:[2,3,0,1] row_mask:0xf bank_mask:0xf bound_ctrl:1
	v_add_u32_dpp v67, v67, v67 quad_perm:[2,3,0,1] row_mask:0xf bank_mask:0xf bound_ctrl:1
	v_add_u32_dpp v64, v64, v64 row_half_mirror row_mask:0xf bank_mask:0xf bound_ctrl:1
	v_add_u32_dpp v65, v65, v65 row_half_mirror row_mask:0xf bank_mask:0xf bound_ctrl:1
	v_add_u32_dpp v66, v66, v66 row_half_mirror row_mask:0xf bank_mask:0xf bound_ctrl:1
	v_add_u32_dpp v67, v67, v67 row_half_mirror row_mask:0xf bank_mask:0xf bound_ctrl:1
	v_cvt_f32_i32_e32 v76, v64
	v_cvt_f32_i32_e32 v77, v65
	v_cvt_f32_i32_e32 v78, v66
	v_cvt_f32_i32_e32 v79, v67
	v_pk_mul_f32 v[76:77], v[52:53], v[76:77] op_sel_hi:[0,1]
	v_pk_mul_f32 v[78:79], v[52:53], v[78:79] op_sel_hi:[0,1]
	v_and_b32_e32 v56, s21, v224
	v_and_b32_e32 v57, s23, v224
	v_and_b32_e32 v58, s21, v228
	v_and_b32_e32 v59, s23, v228
	v_and_b32_e32 v60, s21, v232
	v_and_b32_e32 v61, s23, v232
	v_and_b32_e32 v62, s21, v236
	v_and_b32_e32 v63, s23, v236
	v_mov_b32_e32 v64, v85
	v_mov_b32_e32 v86, 0
	v_mov_b32_e32 v65, v85
	v_mov_b32_e32 v87, 0
	v_mov_b32_e32 v66, v85
	v_mov_b32_e32 v88, 0
	v_mov_b32_e32 v67, v85
	v_mov_b32_e32 v89, 0
	v_dot4c_i32_i8_e32 v64, v56, v32
	v_dot4c_i32_i8_e32 v86, v57, v33
	v_dot4c_i32_i8_e32 v65, v58, v32
	v_dot4c_i32_i8_e32 v87, v59, v33
	v_dot4c_i32_i8_e32 v66, v60, v32
	v_dot4c_i32_i8_e32 v88, v61, v33
	v_dot4c_i32_i8_e32 v67, v62, v32
	v_dot4c_i32_i8_e32 v89, v63, v33
	v_and_b32_e32 v56, s21, v225
	v_and_b32_e32 v57, s23, v225
	v_and_b32_e32 v58, s21, v229
	v_and_b32_e32 v59, s23, v229
	v_and_b32_e32 v60, s21, v233
	v_and_b32_e32 v61, s23, v233
	v_and_b32_e32 v62, s21, v237
	v_and_b32_e32 v63, s23, v237
	v_dot4c_i32_i8_e32 v64, v56, v34
	v_dot4c_i32_i8_e32 v86, v57, v35
	v_dot4c_i32_i8_e32 v65, v58, v34
	v_dot4c_i32_i8_e32 v87, v59, v35
	v_dot4c_i32_i8_e32 v66, v60, v34
	v_dot4c_i32_i8_e32 v88, v61, v35
	v_dot4c_i32_i8_e32 v67, v62, v34
	v_dot4c_i32_i8_e32 v89, v63, v35
	v_and_b32_e32 v56, s21, v226
	v_and_b32_e32 v57, s23, v226
	v_and_b32_e32 v58, s21, v230
	v_and_b32_e32 v59, s23, v230
	v_and_b32_e32 v60, s21, v234
	v_and_b32_e32 v61, s23, v234
	v_and_b32_e32 v62, s21, v238
	v_and_b32_e32 v63, s23, v238
	v_dot4c_i32_i8_e32 v64, v56, v36
	v_dot4c_i32_i8_e32 v86, v57, v37
	v_dot4c_i32_i8_e32 v65, v58, v36
	v_dot4c_i32_i8_e32 v87, v59, v37
	v_dot4c_i32_i8_e32 v66, v60, v36
	v_dot4c_i32_i8_e32 v88, v61, v37
	v_dot4c_i32_i8_e32 v67, v62, v36
	v_dot4c_i32_i8_e32 v89, v63, v37
	v_and_b32_e32 v56, s21, v227
	v_and_b32_e32 v57, s23, v227
	v_and_b32_e32 v58, s21, v231
	v_and_b32_e32 v59, s23, v231
	v_and_b32_e32 v60, s21, v235
	v_and_b32_e32 v61, s23, v235
	v_and_b32_e32 v62, s21, v239
	v_and_b32_e32 v63, s23, v239
	v_dot4c_i32_i8_e32 v64, v56, v38
	v_dot4c_i32_i8_e32 v86, v57, v39
	v_dot4c_i32_i8_e32 v65, v58, v38
	v_dot4c_i32_i8_e32 v87, v59, v39
	v_dot4c_i32_i8_e32 v66, v60, v38
	v_dot4c_i32_i8_e32 v88, v61, v39
	v_dot4c_i32_i8_e32 v67, v62, v38
	v_dot4c_i32_i8_e32 v89, v63, v39
	v_ashrrev_i32_e32 v86, 4, v86
	v_ashrrev_i32_e32 v87, 4, v87
	v_ashrrev_i32_e32 v88, 4, v88
	v_ashrrev_i32_e32 v89, 4, v89
	v_add_u32_e32 v64, v64, v86
	v_add_u32_e32 v65, v65, v87
	v_add_u32_e32 v66, v66, v88
	v_add_u32_e32 v67, v67, v89
	v_add_u32_dpp v64, v64, v64 quad_perm:[1,0,3,2] row_mask:0xf bank_mask:0xf bound_ctrl:1
	v_add_u32_dpp v65, v65, v65 quad_perm:[1,0,3,2] row_mask:0xf bank_mask:0xf bound_ctrl:1
	v_add_u32_dpp v66, v66, v66 quad_perm:[1,0,3,2] row_mask:0xf bank_mask:0xf bound_ctrl:1
	v_add_u32_dpp v67, v67, v67 quad_perm:[1,0,3,2] row_mask:0xf bank_mask:0xf bound_ctrl:1
	v_add_u32_dpp v64, v64, v64 quad_perm:[2,3,0,1] row_mask:0xf bank_mask:0xf bound_ctrl:1
	v_add_u32_dpp v65, v65, v65 quad_perm:[2,3,0,1] row_mask:0xf bank_mask:0xf bound_ctrl:1
	v_add_u32_dpp v66, v66, v66 quad_perm:[2,3,0,1] row_mask:0xf bank_mask:0xf bound_ctrl:1
	v_add_u32_dpp v67, v67, v67 quad_perm:[2,3,0,1] row_mask:0xf bank_mask:0xf bound_ctrl:1
	v_add_u32_dpp v64, v64, v64 row_half_mirror row_mask:0xf bank_mask:0xf bound_ctrl:1
	v_add_u32_dpp v65, v65, v65 row_half_mirror row_mask:0xf bank_mask:0xf bound_ctrl:1
	v_add_u32_dpp v66, v66, v66 row_half_mirror row_mask:0xf bank_mask:0xf bound_ctrl:1
	v_add_u32_dpp v67, v67, v67 row_half_mirror row_mask:0xf bank_mask:0xf bound_ctrl:1
	v_cvt_f32_i32_e32 v80, v64
	v_cvt_f32_i32_e32 v81, v65
	v_cvt_f32_i32_e32 v82, v66
	v_cvt_f32_i32_e32 v83, v67
	v_pk_mul_f32 v[80:81], v[52:53], v[80:81] op_sel_hi:[0,1]
	v_pk_mul_f32 v[82:83], v[52:53], v[82:83] op_sel_hi:[0,1]
	s_lshl_b32 s70, s60, 1
	s_add_u32 s70, s70, s28
	s_lshl_b32 s70, s70, 12
	s_add_u32 s70, s70, s68
	s_mov_b64 s[74:75], exec
	s_and_b64 exec, exec, s[72:73]
	v_add_u32_e32 v9, s70, v5
	global_store_dwordx4 v9, v[68:71], s[64:65]
	global_store_dwordx4 v9, v[72:75], s[64:65] offset:16
	global_store_dwordx4 v9, v[76:79], s[64:65] offset:32
	global_store_dwordx4 v9, v[80:83], s[64:65] offset:48
	s_mov_b64 exec, s[74:75]
	s_mov_b32 s60, s62
	s_cmp_lt_u32 s60, s61
	s_cbranch_scc1 .Lmy_pu0_bodyA

; __device__ __forceinline__ int tid_opaque() { int t = threadIdx.x; asm volatile("" : "+v"(t)); return t; }
; __device__ __forceinline__ void phase_peer_u(const Params& p, int layer, int xs, int wid0, int wstride, char* smraw) {
;   const int tid = tid_opaque(), l = tid & 63, g = l >> 3, j = l & 7;
;   const int wid = wid0 + (tid >> 6);
;   char* xqs = smraw + (tid >> 6) * 256;
;   const int sl = xs >> 1, par = xs & 1;
;   constexpr int TH = T / 2;
;   const unsigned char* Uq = p.Uq + (size_t)(layer * 4 + sl) * NEXP * 128;
;   const unsigned joff = j * 16;
;   u32x4 ni[4];
;   auto load_idx = [&](int tt) {
;     const u32x4* ip = (const u32x4*)((const char*)p.sel_idx + ((unsigned)(2 * tt + par) * 512u + (unsigned)g * 64u));
; #pragma unroll
;     for (int q4 = 0; q4 < 4; ++q4) ni[q4] = ip[q4];
;   };
;   auto issue_rows = [&](int tt, u32x4 (&q)[16], u32x2& xv) {
; #pragma unroll
;     for (int i = 0; i < 16; ++i) q[i] = *(const u32x4*)(Uq + (ni[i >> 2][i & 3] * 128u + joff));
;     xv = *(const u32x2*)((const char*)p.hb + ((unsigned)(2 * tt + par) * 2048u + (unsigned)(sl * 512 + l * 8)));
;   };
;     ...
;   u32x4 qA[16], qB[16]; u32x2 xA = {0u, 0u}, xB = {0u, 0u};
;   int tt = wid;
;   if (tt < TH) { load_idx(tt); issue_rows(tt, qA, xA); if (tt + wstride < TH) load_idx(tt + wstride); }
.LBB0_1265:
	s_or_b64 exec, exec, s[0:1]
	v_mov_b32_e32 v16, v189
	s_barrier
	s_lshl_b64 s[0:1], s[14:15], 21
	s_waitcnt vmcnt(0)
	v_ashrrev_i32_e32 v80, 6, v16
	v_add_u32_e32 v169, s92, v80
	s_add_u32 s15, s0, 0x800000
	s_movk_i32 s2, 0x4020
	s_addc_u32 s20, s1, 0
	v_cmp_gt_i32_e32 vcc, s2, v169
	s_and_saveexec_b64 s[0:1], vcc
	s_cbranch_execz .LBB0_1284
	v_and_b32_e32 v6, 63, v189
	v_lshrrev_b32_e32 v7, 6, v189
	v_lshlrev_b32_e32 v0, 3, v6
	v_and_b32_e32 v1, 7, v6
	v_cmp_eq_u32_e64 s[72:73], 0, v1
	v_lshlrev_b32_e32 v1, 4, v1
	v_lshrrev_b32_e32 v8, 3, v6
	v_readfirstlane_b32 s70, v7
	s_lshl_b32 s71, s28, 9
	v_lshl_add_u32 v2, v8, 6, s71
	v_lshlrev_b32_e32 v5, 6, v8
	v_lshlrev_b32_e32 v3, 8, v7
	v_lshl_add_u32 v4, v1, 1, v3
	v_lshl_add_u32 v3, v6, 2, v3
	s_add_u32 s60, s92, s70
	s_movk_i32 s61, 0x4020
	s_cmp_ge_u32 s60, s61
	s_cbranch_scc1 .Lmy_pu1_done
	s_lshl_b32 s70, s14, 21
	s_add_u32 s70, s70, 0x800000
	s_add_u32 s66, s88, s70
	s_addc_u32 s67, s89, 0
	v_readlane_b32 s64, v254, 4
	v_readlane_b32 s65, v254, 5
	s_lshl_b32 s68, s14, 9
	s_mov_b32 s69, 0x42fe0000
	s_mov_b32 s21, 0xf0f0f0f
	s_mov_b32 s23, 0xf0f0f0f0
	s_lshl_b32 s70, s60, 10
	v_add_u32_e32 v9, s70, v2
	global_load_dwordx4 v[10:13], v9, s[52:53]
	global_load_dwordx4 v[14:17], v9, s[52:53] offset:16
	global_load_dwordx4 v[18:21], v9, s[52:53] offset:32
	global_load_dwordx4 v[22:25], v9, s[52:53] offset:48
	s_waitcnt vmcnt(0)
	v_lshl_add_u32 v6, v10, 7, v1
	global_load_dwordx4 v[106:109], v6, s[66:67]
	v_lshl_add_u32 v7, v11, 7, v1
	global_load_dwordx4 v[110:113], v7, s[66:67]
	v_lshl_add_u32 v6, v12, 7, v1
	global_load_dwordx4 v[114:117], v6, s[66:67]
	v_lshl_add_u32 v7, v13, 7, v1
	global_load_dwordx4 v[118:121], v7, s[66:67]
	v_lshl_add_u32 v6, v14, 7, v1
	global_load_dwordx4 v[122:125], v6, s[66:67]
	v_lshl_add_u32 v7, v15, 7, v1
	global_load_dwordx4 v[126:129], v7, s[66:67]
	v_lshl_add_u32 v6, v16, 7, v1
	global_load_dwordx4 v[130:133], v6, s[66:67]
	v_lshl_add_u32 v7, v17, 7, v1
	global_load_dwordx4 v[134:137], v7, s[66:67]
	v_lshl_add_u32 v6, v18, 7, v1
	global_load_dwordx4 v[138:141], v6, s[66:67]
	v_lshl_add_u32 v7, v19, 7, v1
	global_load_dwordx4 v[142:145], v7, s[66:67]
	v_lshl_add_u32 v6, v20, 7, v1
	global_load_dwordx4 v[146:149], v6, s[66:67]
	v_lshl_add_u32 v7, v21, 7, v1
	global_load_dwordx4 v[150:153], v7, s[66:67]
	v_lshl_add_u32 v6, v22, 7, v1
	global_load_dwordx4 v[154:157], v6, s[66:67]
	v_lshl_add_u32 v7, v23, 7, v1
	global_load_dwordx4 v[158:161], v7, s[66:67]
	v_lshl_add_u32 v6, v24, 7, v1
	global_load_dwordx4 v[162:165], v6, s[66:67]
	v_lshl_add_u32 v7, v25, 7, v1
	global_load_dwordx4 v[166:169], v7, s[66:67]
	s_lshl_b32 s70, s60, 1
	s_add_u32 s70, s70, s28
	s_lshl_b32 s70, s70, 11
	s_add_u32 s70, s70, s68
	v_add_u32_e32 v8, s70, v0
	global_load_dwordx2 v[26:27], v8, s[76:77]
	s_add_u32 s62, s60, s33
	s_cmp_ge_u32 s62, s61
	s_cbranch_scc1 .Lmy_pu1_pro1
	s_lshl_b32 s70, s62, 10
	v_add_u32_e32 v9, s70, v2
	global_load_dwordx4 v[10:13], v9, s[52:53]
	global_load_dwordx4 v[14:17], v9, s[52:53] offset:16
	global_load_dwordx4 v[18:21], v9, s[52:53] offset:32
	global_load_dwordx4 v[22:25], v9, s[52:53] offset:48
